# tmi + FFN-in A operand (H from modulate k0/k11) also tile-major
# baseline (speedup 1.0000x reference)
; #define GAS __attribute__((address_space(1)))
; __device__ __forceinline__ void modulate_phase(Frame& F, const float* x, bf16* H, const float* gnorm, const float* modsub) {
;     const int gw = F.vcu * NWAVES + F.wave, NGW = F.G * NWAVES, per = (M + NGW - 1) / NGW;
;     const int rbeg = gw * per, rend = min(rbeg + per, M);
;     if (rbeg >= rend) return;
;     f32x4 gs[8], sh[8]; int curb = -1;
;     f32x4 v[8], nv[8];
;     { const GAS f32x4* xr = (const GAS f32x4*)(x + (size_t)rbeg * D) + F.lane;
; #pragma unroll
;       for (int j = 0; j < 8; ++j) v[j] = xr[64 * j]; }
; #pragma unroll 1
;     for (int r = rbeg; r < rend; ++r) {
;         { const GAS f32x4* xn = (const GAS f32x4*)(x + (size_t)min(r + 1, rend - 1) * D) + F.lane;
; #pragma unroll
;           for (int j = 0; j < 8; ++j) nv[j] = xn[64 * j]; }
;         const int b = r >> 12;
;         if (b != curb) { curb = b;
; #pragma unroll
;             for (int j = 0; j < 8; ++j) { const int c = 4 * F.lane + 256 * j;
;                 const f32x4 g = *(const GAS f32x4*)(gnorm + c), sc = *(const GAS f32x4*)(modsub + (size_t)b * NMOD + D + c);
;                 gs[j] = g * (sc + 1.0f); sh[j] = *(const GAS f32x4*)(modsub + (size_t)b * NMOD + c); } }
;         float s = 0.f;
; #pragma unroll
;         for (int j = 0; j < 8; ++j) s += (v[j].x * v[j].x + v[j].y * v[j].y) + (v[j].z * v[j].z + v[j].w * v[j].w);
;         const float rstd = 1.0f / sqrtf(wave_sum(s) * (1.0f / D) + RMS_EPS);
.LBB0_214:
	s_ashr_i32 s2, s2, 6
	s_add_i32 s2, s2, s74
	v_readlane_b32 s7, v255, 0
	s_mul_i32 s6, s7, s2
	s_add_i32 s2, s6, s7
	v_readlane_b32 s10, v255, 42
	s_min_i32 s2, s2, 0x4000
	v_readlane_b32 s11, v255, 43
	s_cmp_ge_i32 s6, s2
	s_cbranch_scc1 .LBB0_219
	s_mul_i32 s7, s78, 0x48000
	s_add_u32 s7, s8, s7
	s_addc_u32 s12, s9, 0
	s_add_u32 s14, s7, 0x100000
	s_addc_u32 s15, s12, 0
	s_mul_i32 s7, s78, 0x6000
	s_add_u32 s12, s10, s7
	s_addc_u32 s13, s11, 0
	s_ashr_i32 s7, s6, 31
	s_lshl_b64 s[10:11], s[6:7], 13
	s_waitcnt vmcnt(0)
	v_and_b32_e32 v130, 63, v0
	s_add_u32 s10, s0, s10
	s_addc_u32 s11, s1, s11
	v_lshlrev_b32_e32 v0, 4, v130
	v_lshl_add_u64 v[2:3], s[10:11], 0, v[0:1]
	global_load_dwordx4 v[94:97], v0, s[10:11]
	global_load_dwordx4 v[90:93], v0, s[10:11] offset:1024
	global_load_dwordx4 v[54:57], v0, s[10:11] offset:2048
	global_load_dwordx4 v[42:45], v0, s[10:11] offset:3072
	s_movk_i32 s10, 0x1000
	v_add_co_u32_e32 v2, vcc, s10, v2
	v_lshl_add_u64 v[132:133], s[12:13], 0, v[0:1]
	s_nop 0
	v_addc_co_u32_e32 v3, vcc, 0, v3, vcc
	global_load_dwordx4 v[30:33], v[2:3], off
	global_load_dwordx4 v[26:29], v[2:3], off offset:1024
	global_load_dwordx4 v[14:17], v[2:3], off offset:2048
	global_load_dwordx4 v[10:13], v[2:3], off offset:3072
	v_lshlrev_b32_e32 v2, 2, v130
	v_or_b32_e32 v18, 0x400, v2
	v_or_b32_e32 v20, 0x500, v2
	v_lshlrev_b32_e32 v0, 2, v18
	v_or_b32_e32 v22, 0x600, v2
	v_lshl_add_u64 v[134:135], s[12:13], 0, v[0:1]
	v_lshlrev_b32_e32 v0, 2, v20
	v_or_b32_e32 v24, 0x700, v2
	v_lshl_add_u64 v[136:137], s[12:13], 0, v[0:1]
	v_lshlrev_b32_e32 v0, 2, v22
	v_lshl_add_u64 v[138:139], s[12:13], 0, v[0:1]
	v_lshlrev_b32_e32 v0, 2, v24
	s_add_i32 s16, s2, -1
	v_lshl_add_u64 v[140:141], s[12:13], 0, v[0:1]
	s_lshr_b32 s12, s6, 8
	s_lshl_b32 s12, s12, 20
	s_and_b32 s13, s6, 0xff
	s_lshl_b32 s13, s13, 7
	s_add_u32 s12, s12, s13
	s_mov_b32 s13, 0
	s_add_u32 s7, s8, s12
	s_addc_u32 s9, s9, s13
	v_or_b32_e32 v4, 0x100, v2
	v_or_b32_e32 v6, 0x200, v2
	v_or_b32_e32 v8, 0x300, v2
	s_add_u32 s8, s7, 0x1ed90000
	s_mov_b32 s10, -1
	s_addc_u32 s9, s9, 0
	v_lshlrev_b32_e32 v131, 2, v2
	v_lshlrev_b32_e32 v142, 2, v4
	v_lshlrev_b32_e32 v143, 2, v6
	v_lshlrev_b32_e32 v144, 2, v8
	v_lshlrev_b32_e32 v145, 2, v18
	v_lshlrev_b32_e32 v146, 2, v20
	v_lshlrev_b32_e32 v147, 2, v22
	v_lshlrev_b32_e32 v148, 2, v24
	s_branch .LBB0_217
.LBB0_216:
	s_waitcnt vmcnt(8)
	v_mul_f32_e32 v0, v95, v95
	v_mul_f32_e32 v149, v97, v97
	v_fmac_f32_e32 v0, v94, v94
	v_fmac_f32_e32 v149, v96, v96
	v_add_f32_e32 v0, v0, v149
	v_mul_f32_e32 v149, v91, v91
	v_mul_f32_e32 v150, v93, v93
	v_fmac_f32_e32 v149, v90, v90
	v_fmac_f32_e32 v150, v92, v92
	v_add_f32_e32 v149, v149, v150
	v_add_f32_e32 v0, v0, v149
	v_mul_f32_e32 v149, v55, v55
	v_mul_f32_e32 v150, v57, v57
	v_fmac_f32_e32 v149, v54, v54
	v_fmac_f32_e32 v150, v56, v56
	v_add_f32_e32 v149, v149, v150
	v_add_f32_e32 v0, v149, v0
	v_mul_f32_e32 v149, v43, v43
	v_mul_f32_e32 v150, v45, v45
	v_fmac_f32_e32 v149, v42, v42
	v_fmac_f32_e32 v150, v44, v44
	v_add_f32_e32 v149, v149, v150
	v_add_f32_e32 v0, v149, v0
	v_mul_f32_e32 v149, v31, v31
	v_mul_f32_e32 v150, v33, v33
	v_fmac_f32_e32 v149, v30, v30
	v_fmac_f32_e32 v150, v32, v32
	v_add_f32_e32 v149, v149, v150
	v_add_f32_e32 v0, v149, v0
	v_mul_f32_e32 v149, v27, v27
	v_mul_f32_e32 v150, v29, v29
	v_fmac_f32_e32 v149, v26, v26
	v_fmac_f32_e32 v150, v28, v28
	v_add_f32_e32 v149, v149, v150
	v_add_f32_e32 v0, v149, v0
	v_mul_f32_e32 v149, v15, v15
	v_mul_f32_e32 v150, v17, v17
	v_fmac_f32_e32 v149, v14, v14
	v_fmac_f32_e32 v150, v16, v16
	v_add_f32_e32 v149, v149, v150
	v_add_f32_e32 v0, v149, v0
	v_mul_f32_e32 v149, v11, v11
	v_mul_f32_e32 v150, v13, v13
	v_fmac_f32_e32 v149, v10, v10
	v_fmac_f32_e32 v150, v12, v12
	v_add_f32_e32 v149, v149, v150
	v_add_f32_e32 v0, v149, v0
	ds_swizzle_b32 v149, v0 offset:swizzle(SWAP,1)
	s_waitcnt lgkmcnt(0)
	v_add_f32_e32 v0, v0, v149
	ds_swizzle_b32 v149, v0 offset:swizzle(SWAP,2)
	s_waitcnt lgkmcnt(0)
	v_add_f32_e32 v0, v0, v149
	ds_swizzle_b32 v149, v0 offset:swizzle(SWAP,4)
	s_waitcnt lgkmcnt(0)
	v_add_f32_e32 v0, v0, v149
	ds_swizzle_b32 v149, v0 offset:swizzle(SWAP,8)
	s_waitcnt lgkmcnt(0)
	v_add_f32_e32 v0, v0, v149
	ds_swizzle_b32 v149, v0 offset:swizzle(SWAP,16)
	s_waitcnt lgkmcnt(0)
; #define GAS __attribute__((address_space(1)))
; __device__ __forceinline__ unsigned pk2(float lo, float hi) { return f2bf(lo) | (f2bf(hi) << 16); }
; __device__ __forceinline__ void modulate_phase(Frame& F, const float* x, bf16* H, const float* gnorm, const float* modsub) {
;     ...
;         const float rstd = 1.0f / sqrtf(wave_sum(s) * (1.0f / D) + RMS_EPS);
;         GAS unsigned long long* o8 = (GAS unsigned long long*)(H + (size_t)r * D) + F.lane;
; #pragma unroll
;         for (int j = 0; j < 8; ++j) { const f32x4 y = v[j] * rstd * gs[j] + sh[j];
;             o8[64 * j] = (unsigned long long)pk2(y.x, y.y) | ((unsigned long long)pk2(y.z, y.w) << 32); }
	v_add_f32_e32 v0, v0, v149
	v_mov_b32_e32 v149, v0
	s_nop 1
	v_permlane32_swap_b32_e32 v0, v149
	v_add_f32_e32 v0, v0, v149
	v_fmamk_f32 v0, v0, 0x3a000000, v202
	v_mul_f32_e32 v149, 0x4f800000, v0
	v_cmp_gt_f32_e32 vcc, s60, v0
	s_nop 1
	v_cndmask_b32_e32 v0, v0, v149, vcc
	v_sqrt_f32_e32 v149, v0
	s_nop 0
	v_add_u32_e32 v150, -1, v149
	v_fma_f32 v151, -v150, v149, v0
	v_cmp_ge_f32_e64 s[36:37], 0, v151
	v_add_u32_e32 v151, 1, v149
	s_nop 0
	v_cndmask_b32_e64 v150, v149, v150, s[36:37]
	v_fma_f32 v149, -v151, v149, v0
	v_cmp_lt_f32_e64 s[36:37], 0, v149
	s_nop 1
	v_cndmask_b32_e64 v149, v150, v151, s[36:37]
	v_mul_f32_e32 v150, 0x37800000, v149
	v_cndmask_b32_e32 v149, v149, v150, vcc
	v_cmp_class_f32_e32 vcc, v0, v203
	s_nop 1
	v_cndmask_b32_e32 v0, v149, v0, vcc
	v_div_scale_f32 v149, s[12:13], v0, v0, 1.0
	v_rcp_f32_e32 v150, v149
	s_nop 0
	v_fma_f32 v151, -v149, v150, 1.0
	v_fmac_f32_e32 v150, v151, v150
	v_div_scale_f32 v151, vcc, 1.0, v0, 1.0
	v_mul_f32_e32 v152, v151, v150
	v_fma_f32 v153, -v149, v152, v151
	v_fmac_f32_e32 v152, v153, v150
	v_fma_f32 v149, -v149, v152, v151
	v_div_fmas_f32 v149, v149, v150, v152
	v_div_fixup_f32 v0, v149, v0, 1.0
	v_pk_mul_f32 v[94:95], v[94:95], v[0:1] op_sel_hi:[1,0]
	v_pk_mul_f32 v[96:97], v[96:97], v[0:1] op_sel_hi:[1,0]
	v_pk_fma_f32 v[94:95], v[2:3], v[94:95], v[6:7]
	v_pk_fma_f32 v[96:97], v[4:5], v[96:97], v[8:9]
	v_bfe_u32 v150, v94, 16, 1
	v_add3_u32 v94, v94, v150, s94
	v_bfe_u32 v150, v95, 16, 1
	v_lshrrev_b32_e32 v94, 16, v94
	v_add3_u32 v95, v95, v150, s94
	v_and_or_b32 v94, v95, s95, v94
	v_bfe_u32 v95, v96, 16, 1
	v_add3_u32 v95, v96, v95, s94
	v_bfe_u32 v96, v97, 16, 1
	v_lshrrev_b32_e32 v95, 16, v95
	v_add3_u32 v96, v97, v96, s94
	v_pk_mul_f32 v[90:91], v[90:91], v[0:1] op_sel_hi:[1,0]
	v_lshrrev_b32_e32 v149, 4, v130
	v_lshlrev_b32_e32 v149, 15, v149
	v_and_b32_e32 v200, 15, v130
	v_lshl_or_b32 v149, v200, 3, v149
	v_and_or_b32 v95, v96, s95, v95
	v_pk_fma_f32 v[90:91], v[22:23], v[90:91], v[18:19]
	global_store_dwordx2 v149, v[94:95], s[8:9]
	v_bfe_u32 v94, v90, 16, 1
	v_pk_mul_f32 v[92:93], v[92:93], v[0:1] op_sel_hi:[1,0]
	v_add3_u32 v90, v90, v94, s94
	v_bfe_u32 v94, v91, 16, 1
	v_pk_fma_f32 v[92:93], v[24:25], v[92:93], v[20:21]
	v_lshrrev_b32_e32 v90, 16, v90
	v_add3_u32 v91, v91, v94, s94
	v_and_or_b32 v90, v91, s95, v90
	v_bfe_u32 v91, v92, 16, 1
	v_add3_u32 v91, v92, v91, s94
	v_bfe_u32 v92, v93, 16, 1
	v_lshrrev_b32_e32 v91, 16, v91
	v_add3_u32 v92, v93, v92, s94
	v_pk_mul_f32 v[54:55], v[54:55], v[0:1] op_sel_hi:[1,0]
	v_and_or_b32 v91, v92, s95, v91
	v_pk_fma_f32 v[54:55], v[38:39], v[54:55], v[34:35]
	s_add_u32 s8, s8, 0x20000
	s_addc_u32 s9, s9, 0
	global_store_dwordx2 v149, v[90:91], s[8:9]
	v_bfe_u32 v90, v54, 16, 1
	v_pk_mul_f32 v[56:57], v[56:57], v[0:1] op_sel_hi:[1,0]
	v_add3_u32 v54, v54, v90, s94
	v_bfe_u32 v90, v55, 16, 1
	v_pk_fma_f32 v[56:57], v[40:41], v[56:57], v[36:37]
	v_lshrrev_b32_e32 v54, 16, v54
	v_add3_u32 v55, v55, v90, s94
	v_and_or_b32 v54, v55, s95, v54
	v_bfe_u32 v55, v56, 16, 1
	v_add3_u32 v55, v56, v55, s94
	v_bfe_u32 v56, v57, 16, 1
	v_lshrrev_b32_e32 v55, 16, v55
	v_add3_u32 v56, v57, v56, s94
	v_pk_mul_f32 v[42:43], v[42:43], v[0:1] op_sel_hi:[1,0]
	v_and_or_b32 v55, v56, s95, v55
	v_pk_fma_f32 v[42:43], v[86:87], v[42:43], v[78:79]
	s_add_u32 s8, s8, 0x20000
	s_addc_u32 s9, s9, 0
	global_store_dwordx2 v149, v[54:55], s[8:9]
	v_bfe_u32 v54, v42, 16, 1
	v_pk_mul_f32 v[44:45], v[44:45], v[0:1] op_sel_hi:[1,0]
	v_add3_u32 v42, v42, v54, s94
	v_bfe_u32 v54, v43, 16, 1
	v_pk_fma_f32 v[44:45], v[88:89], v[44:45], v[80:81]
	v_lshrrev_b32_e32 v42, 16, v42
	v_add3_u32 v43, v43, v54, s94
	v_and_or_b32 v42, v43, s95, v42
	v_bfe_u32 v43, v44, 16, 1
	v_add3_u32 v43, v44, v43, s94
	v_bfe_u32 v44, v45, 16, 1
	v_lshrrev_b32_e32 v43, 16, v43
	v_add3_u32 v44, v45, v44, s94
	v_pk_mul_f32 v[30:31], v[30:31], v[0:1] op_sel_hi:[1,0]
	v_and_or_b32 v43, v44, s95, v43
	v_pk_fma_f32 v[30:31], v[102:103], v[30:31], v[98:99]
	s_add_u32 s8, s8, 0x20000
	s_addc_u32 s9, s9, 0
	global_store_dwordx2 v149, v[42:43], s[8:9]
	v_bfe_u32 v42, v30, 16, 1
	v_pk_mul_f32 v[32:33], v[32:33], v[0:1] op_sel_hi:[1,0]
	v_add3_u32 v30, v30, v42, s94
	v_bfe_u32 v42, v31, 16, 1
	v_pk_fma_f32 v[32:33], v[104:105], v[32:33], v[100:101]
	v_lshrrev_b32_e32 v30, 16, v30
	v_add3_u32 v31, v31, v42, s94
	v_and_or_b32 v30, v31, s95, v30
	v_bfe_u32 v31, v32, 16, 1
	v_add3_u32 v31, v32, v31, s94
	v_bfe_u32 v32, v33, 16, 1
	v_lshrrev_b32_e32 v31, 16, v31
	v_add3_u32 v32, v33, v32, s94
	v_pk_mul_f32 v[26:27], v[26:27], v[0:1] op_sel_hi:[1,0]
	v_and_or_b32 v31, v32, s95, v31
	v_pk_fma_f32 v[26:27], v[110:111], v[26:27], v[106:107]
	s_add_u32 s8, s8, 0x20000
	s_addc_u32 s9, s9, 0
	global_store_dwordx2 v149, v[30:31], s[8:9]
	v_bfe_u32 v30, v26, 16, 1
	v_pk_mul_f32 v[28:29], v[28:29], v[0:1] op_sel_hi:[1,0]
	v_add3_u32 v26, v26, v30, s94
	v_bfe_u32 v30, v27, 16, 1
	v_pk_fma_f32 v[28:29], v[112:113], v[28:29], v[108:109]
	v_lshrrev_b32_e32 v26, 16, v26
	v_add3_u32 v27, v27, v30, s94
	v_and_or_b32 v26, v27, s95, v26
	v_bfe_u32 v27, v28, 16, 1
	v_add3_u32 v27, v28, v27, s94
	v_bfe_u32 v28, v29, 16, 1
	v_lshrrev_b32_e32 v27, 16, v27
	v_add3_u32 v28, v29, v28, s94
	v_pk_mul_f32 v[14:15], v[14:15], v[0:1] op_sel_hi:[1,0]
	v_pk_mul_f32 v[10:11], v[10:11], v[0:1] op_sel_hi:[1,0]
	v_and_or_b32 v27, v28, s95, v27
	v_pk_fma_f32 v[14:15], v[118:119], v[14:15], v[114:115]
	v_pk_fma_f32 v[10:11], v[122:123], v[10:11], v[126:127]
	s_add_u32 s8, s8, 0x20000
	s_addc_u32 s9, s9, 0
	global_store_dwordx2 v149, v[26:27], s[8:9]
	v_pk_mul_f32 v[16:17], v[16:17], v[0:1] op_sel_hi:[1,0]
	v_bfe_u32 v26, v14, 16, 1
	v_pk_mul_f32 v[12:13], v[12:13], v[0:1] op_sel_hi:[1,0]
	v_bfe_u32 v0, v10, 16, 1
	v_add3_u32 v14, v14, v26, s94
	v_bfe_u32 v26, v15, 16, 1
	v_add3_u32 v0, v10, v0, s94
	v_bfe_u32 v10, v11, 16, 1
	v_pk_fma_f32 v[16:17], v[120:121], v[16:17], v[116:117]
	v_lshrrev_b32_e32 v14, 16, v14
	v_add3_u32 v15, v15, v26, s94
	v_pk_fma_f32 v[12:13], v[124:125], v[12:13], v[128:129]
	v_lshrrev_b32_e32 v0, 16, v0
	v_add3_u32 v10, v11, v10, s94
	v_and_or_b32 v14, v15, s95, v14
	v_bfe_u32 v15, v16, 16, 1
	v_and_or_b32 v10, v10, s95, v0
	v_bfe_u32 v0, v12, 16, 1
	v_add3_u32 v15, v16, v15, s94
	v_bfe_u32 v16, v17, 16, 1
	v_add3_u32 v0, v12, v0, s94
	v_bfe_u32 v11, v13, 16, 1
	v_lshrrev_b32_e32 v15, 16, v15
	v_add3_u32 v16, v17, v16, s94
	v_lshrrev_b32_e32 v0, 16, v0
	v_add3_u32 v11, v13, v11, s94
	v_and_or_b32 v15, v16, s95, v15
	v_and_or_b32 v11, v11, s95, v0
	s_add_u32 s8, s8, 0x20000
	s_addc_u32 s9, s9, 0
	global_store_dwordx2 v149, v[14:15], s[8:9]
	s_add_u32 s8, s8, 0x20000
	s_addc_u32 s9, s9, 0
	global_store_dwordx2 v149, v[10:11], s[8:9]
	s_sub_u32 s8, s8, 0xdff80
	s_subb_u32 s9, s9, 0
	s_cmp_lt_i32 s6, s2
	s_waitcnt vmcnt(8)
; __device__ __forceinline__ void modulate_phase(Frame& F, const float* x, bf16* H, const float* gnorm, const float* modsub) {
;     ...
;         for (int j = 0; j < 8; ++j) v[j] = nv[j];
;     }
	v_mov_b32_e32 v94, v82
	v_mov_b32_e32 v95, v83
	v_mov_b32_e32 v96, v84
	v_mov_b32_e32 v97, v85
	v_mov_b32_e32 v90, v74
	v_mov_b32_e32 v91, v75
	v_mov_b32_e32 v92, v76
	v_mov_b32_e32 v93, v77
	v_mov_b32_e32 v54, v66
	v_mov_b32_e32 v55, v67
	v_mov_b32_e32 v56, v68
	v_mov_b32_e32 v57, v69
	v_mov_b32_e32 v42, v58
	v_mov_b32_e32 v43, v59
	v_mov_b32_e32 v44, v60
	v_mov_b32_e32 v45, v61
	v_mov_b32_e32 v30, v70
	v_mov_b32_e32 v31, v71
	v_mov_b32_e32 v32, v72
	v_mov_b32_e32 v33, v73
	v_mov_b32_e32 v26, v62
	v_mov_b32_e32 v27, v63
	v_mov_b32_e32 v28, v64
	v_mov_b32_e32 v29, v65
	v_mov_b32_e32 v14, v50
	v_mov_b32_e32 v15, v51
	v_mov_b32_e32 v16, v52
	v_mov_b32_e32 v17, v53
	v_mov_b32_e32 v10, v46
	v_mov_b32_e32 v11, v47
	v_mov_b32_e32 v12, v48
	v_mov_b32_e32 v13, v49
	s_cbranch_scc0 .LBB0_219

; template <class Epi, class Sched, bool ALIGN_EPI = false, bool SP2 = false>
; __device__ __forceinline__ void gemm_phase(PG8_LAS unsigned char* lds, const Gemm g, const Sched& S, const Epi& E, int wave_s) {
;     int tid_ = (wave_s << 6) | fresh_lane(); asm volatile("" : "+v"(tid_));
;     const int tid = tid_, wid = __builtin_amdgcn_readfirstlane(tid >> 6), lane = tid & 63, wr = wid >> 2, wc = wid & 3, fr = lane & 15, fq = lane >> 4;
;     const int K = g.K, nt = K / BK;
;     unsigned voffA[2], voffB[2];
; #pragma unroll
;     for (int i = 0; i < 2; ++i) { int R, C; stage_rc(tid * 16 + i * 8192, R, C); const int Rb = Epi::PERM ? ((R & ~31) + perm32(R & 31)) : R;
;         voffA[i] = (unsigned)(R * g.lda + C) * 2u; voffB[i] = (unsigned)(Rb * g.ldb + C) * 2u; }
;     const size_t kstep = (size_t)(BK * 2);
;     const size_t hstepA = (size_t)HALF * g.lda * 2, hstepB = (size_t)HALF * g.ldb * 2;
;     const size_t tstepA = 2 * hstepA, tstepB = 2 * hstepB;
;     const unsigned ldsw = (unsigned)wid * 1024u;
;     const int aoff = lds_byte(wr * 64 + fr, fq * 8), boff = lds_byte(wc * 32 + fr, fq * 8);
;     ...
;     Unit cur, nxt; int ui = 0;
;     if (!S.next(0, cur)) return;
;     f32x4 acc[2][2][4][2];
; #pragma unroll
;     for (int a = 0; a < 2; ++a)
; #pragma unroll
;         for (int b = 0; b < 2; ++b)
; #pragma unroll
;             for (int m = 0; m < 4; ++m)
; #pragma unroll
;                 for (int n = 0; n < 2; ++n) acc[a][b][m][n] = (f32x4){0.f, 0.f, 0.f, 0.f};
;     bf16x8 At[4][2], B0[2][2], B1[2][2];
;     const char* cA = (const char*)g.A + (size_t)cur.pm * tstepA; const char* cB = (const char*)g.Bt + (size_t)cur.pn * tstepB;
;     S.a_ready(cur);
;     if constexpr (SP2) {
;         PG8_STAGE(PG8_SB(0, 0), cB, voffB); PG8_STAGE(PG8_SB(0, 1), cB + hstepB, voffB); PG8_STAGE(PG8_SA(0, 0), cA, voffA); PG8_STAGE(PG8_SA(0, 1), cA + hstepA, voffA);
;         if (wr == 1) PG8_BAR;
;         PG8_WAIT_V(2); PG8_BAR;
;         PG8_STAGE(PG8_SB(1, 0), cB + kstep, voffB); PG8_STAGE(PG8_SA(1, 0), cA + kstep, voffA); PG8_STAGE(PG8_SB(1, 1), cB + hstepB + kstep, voffB);
;         PG8_WAIT_V(6); PG8_BAR;
;     } else {
;         PG8_STAGE(PG8_SB(0, 0), cB, voffB); PG8_STAGE(PG8_SA(0, 0), cA, voffA); PG8_STAGE(PG8_SB(0, 1), cB + hstepB, voffB); PG8_STAGE(PG8_SA(0, 1), cA + hstepA, voffA);
;         if (wr == 1) PG8_BAR;
;         PG8_WAIT_V(4); PG8_BAR;
.LBB0_269:
	s_andn2_b64 vcc, exec, s[0:1]
	v_readlane_b32 s0, v254, 0
	v_readlane_b32 s1, v254, 1
	s_nop 1
	v_cndmask_b32_e64 v0, 0, 1, s[0:1]
	v_cmp_ne_u32_e64 s[0:1], 1, v0
	s_nop 1
	v_writelane_b32 v255, s0, 49
	s_nop 1
	v_writelane_b32 v255, s1, 50
	s_cbranch_vccnz .LBB0_334
	s_load_dwordx2 s[6:7], s[82:83], 0xb8
	v_mov_b32_e32 v0, v1
	s_waitcnt lgkmcnt(0)
	v_readlane_b32 s0, v253, 21
	v_mbcnt_lo_u32_b32 v0, -1, v0
	v_mbcnt_hi_u32_b32 v0, -1, v0
	v_or_b32_e32 v0, s0, v0
	s_nop 0
	v_readfirstlane_b32 s0, v0
	v_mov_b32_e32 v0, v1
	s_andn2_b32 s0, s0, 63
	v_mbcnt_lo_u32_b32 v0, -1, v0
	v_mbcnt_hi_u32_b32 v0, -1, v0
	v_or_b32_e32 v16, s0, v0
	v_readlane_b32 s0, v255, 49
	v_readlane_b32 s1, v255, 50
	s_and_b64 vcc, exec, s[0:1]
	v_readfirstlane_b32 s8, v16
	s_cbranch_vccnz .LBB0_286
	v_lshlrev_b32_e32 v0, 4, v16
	v_add_u32_e32 v2, 0x2000, v0
	v_ashrrev_i32_e32 v3, 31, v2
	v_lshrrev_b32_e32 v3, 22, v3
	v_add_u32_e32 v3, v2, v3
	v_ashrrev_i32_e32 v10, 10, v3
	v_mul_i32_i24_e32 v3, 0x400, v10
	v_sub_u32_e32 v2, v2, v3
	v_lshrrev_b32_e32 v3, 4, v2
	v_bitop3_b32 v2, v3, v2, 32 bitop3:0x6c
	v_ashrrev_i32_e32 v3, 31, v2
	s_add_u32 s2, s6, 0x1ed90000
	v_lshrrev_b32_e32 v3, 26, v3
	s_addc_u32 s22, s7, 0
	s_mul_i32 s0, s78, 0x5800000
	v_add_u32_e32 v3, v2, v3
	v_lshlrev_b32_e32 v4, 3, v10
	s_add_u32 s0, s6, s0
	v_ashrrev_i32_e32 v11, 6, v3
	v_and_b32_e32 v4, -16, v4
	s_addc_u32 s1, s7, 0
	v_add_u32_e32 v4, v11, v4
	s_add_u32 s36, s0, 0x190000
	v_and_b32_e32 v5, 3, v11
	s_mov_b32 s0, 0xfffe0
	v_lshrrev_b32_e32 v6, 2, v4
	v_lshlrev_b32_e32 v7, 1, v4
	v_and_or_b32 v5, v4, s0, v5
	v_and_b32_e32 v6, 4, v6
	v_and_b32_e32 v7, 24, v7
	v_and_b32_e32 v3, 0xc0, v3
	v_or3_b32 v5, v5, v6, v7
	v_sub_u32_e32 v2, v2, v3
	v_mov_b32_e32 v7, 1
	v_lshlrev_b32_e32 v6, 5, v10
	v_ashrrev_i16_sdwa v2, v7, sext(v2) dst_sel:DWORD dst_unused:UNUSED_PAD src0_sel:DWORD src1_sel:BYTE_0
	v_and_b32_e32 v6, 32, v6
	v_bfe_i32 v12, v2, 0, 16
	v_add_lshl_u32 v2, v6, v12, 1
	s_waitcnt vmcnt(0)
	v_lshl_add_u32 v130, v5, 7, v2
	v_lshl_add_u32 v132, v4, 7, v2
	v_bfe_i32 v2, v16, 27, 1
	v_lshrrev_b32_e32 v2, 22, v2
	v_add_u32_e32 v2, v0, v2
	v_and_b32_e32 v2, 0xfffffc00, v2
	v_sub_u32_e32 v0, v0, v2
	v_lshrrev_b32_e32 v2, 4, v0
	v_ashrrev_i32_e32 v3, 31, v16
	v_bitop3_b32 v0, v2, v0, 32 bitop3:0x6c
	v_lshrrev_b32_e32 v3, 26, v3
	v_ashrrev_i32_e32 v2, 31, v0
	v_add_u32_e32 v3, v16, v3
	v_lshrrev_b32_e32 v2, 26, v2
	v_ashrrev_i32_e32 v14, 6, v3
	v_add_u32_e32 v2, v0, v2
	v_lshlrev_b32_e32 v3, 3, v14
	v_ashrrev_i32_e32 v13, 6, v2
	v_and_b32_e32 v3, -16, v3
	v_add_u32_e32 v3, v13, v3
	v_and_b32_e32 v4, 3, v13
	v_lshrrev_b32_e32 v5, 2, v3
	v_lshlrev_b32_e32 v6, 1, v3
	v_and_b32_e32 v2, 0xc0, v2
	s_addc_u32 s37, s1, 0
	s_ashr_i32 s9, s8, 6
	v_and_or_b32 v4, v3, s0, v4
	v_and_b32_e32 v5, 4, v5
	v_and_b32_e32 v6, 24, v6
	v_sub_u32_e32 v0, v0, v2
	s_ashr_i32 s10, s8, 8
	s_lshl_b32 s40, s9, 10
	v_or3_b32 v4, v4, v5, v6
	v_lshlrev_b32_e32 v5, 5, v14
	v_ashrrev_i16_sdwa v0, v7, sext(v0) dst_sel:DWORD dst_unused:UNUSED_PAD src0_sel:DWORD src1_sel:BYTE_0
	v_readlane_b32 s0, v254, 47
	v_and_b32_e32 v5, 32, v5
	v_bfe_i32 v15, v0, 0, 16
	v_readlane_b32 s1, v254, 48
	s_add_u32 s18, s36, s0
	v_add_lshl_u32 v2, v5, v15, 1
	s_addc_u32 s19, s37, s1
	s_add_i32 s41, s40, 0
	v_lshl_add_u32 v0, v4, 7, v2
	s_add_i32 m0, s41, 0x10000
	v_lshl_add_u32 v134, v3, 7, v2
	global_load_lds_dwordx4 v0, s[18:19]
	s_add_i32 m0, s41, 0x12000
	s_add_u32 s0, s18, 0x4000
	global_load_lds_dwordx4 v130, s[18:19]
	s_addc_u32 s1, s19, 0
	s_add_i32 m0, s41, 0x14000
	v_mov_b32_e32 v131, v1
	global_load_lds_dwordx4 v0, s[0:1]
	s_add_i32 m0, s41, 0x16000
	v_mov_b32_e32 v135, v1
	global_load_lds_dwordx4 v130, s[0:1]
	v_readlane_b32 s0, v254, 56
	v_readlane_b32 s1, v254, 57
	s_add_u32 s20, s2, s0
	s_addc_u32 s21, s22, s1
	s_add_i32 s42, s41, 0x2000
	s_mov_b32 m0, s41
	s_add_u32 s0, s20, 0x4000
	global_load_lds_dwordx4 v134, s[20:21]
	s_mov_b32 m0, s42
	s_addc_u32 s1, s21, 0
	s_add_i32 s43, s41, 0x4000
	global_load_lds_dwordx4 v132, s[20:21]
	s_mov_b32 m0, s43
	s_add_i32 s44, s41, 0x6000
	global_load_lds_dwordx4 v134, s[0:1]
	s_mov_b32 m0, s44
	v_mov_b32_e32 v133, v1
	global_load_lds_dwordx4 v132, s[0:1]
	s_cmp_eq_u32 s10, 1
	v_lshl_add_u64 v[8:9], s[18:19], 0, v[0:1]
	v_lshl_add_u64 v[6:7], s[18:19], 0, v[130:131]
	v_lshl_add_u64 v[2:3], s[20:21], 0, v[134:135]
	s_cselect_b64 s[0:1], -1, 0
	s_cmp_lg_u32 s10, 1
	v_lshl_add_u64 v[4:5], s[20:21], 0, v[132:133]
	s_cbranch_scc1 .LBB0_273
	s_barrier
.LBB0_273:
	s_add_u32 s6, s6, 0x22d90000
	v_lshrrev_b32_e32 v18, 1, v16
	s_addc_u32 s7, s7, 0
	v_and_b32_e32 v18, 24, v18
	s_lshl_b32 s9, s9, 5
	v_and_b32_e32 v17, 15, v16
	v_lshlrev_b32_e32 v19, 1, v18
	v_lshlrev_b32_e32 v16, 2, v16
	s_and_b32 s12, s9, 0x60
	s_add_i32 m0, s41, 0x18000
	s_mov_b64 s[100:101], 0x8000
	v_lshl_add_u64 v[8:9], v[8:9], 0, s[100:101]
	v_lshl_or_b32 v142, s10, 6, v17
	v_lshl_or_b32 v17, v17, 6, v19
	s_lshl_b32 s10, s10, 13
	v_and_b32_e32 v16, 32, v16
	s_lshl_b32 s9, s12, 7
	s_waitcnt vmcnt(2)
	s_barrier
	global_load_lds_dwordx4 v[8:9], off
	v_lshl_add_u64 v[6:7], v[6:7], 0, s[100:101]
	s_add_i32 m0, s41, 0x1a000
	s_add_i32 s45, s41, 0x8000
	s_add_i32 s46, s41, 0xa000
	v_bitop3_b32 v19, v17, s10, v16 bitop3:0xde
	global_load_lds_dwordx4 v[6:7], off
	s_mov_b64 s[100:101], 0x8000
	v_lshl_add_u64 v[2:3], v[2:3], 0, s[100:101]
	s_mov_b32 m0, s45
	s_add_u32 s10, s18, 0xc000
	global_load_lds_dwordx4 v[2:3], off
	v_lshl_add_u64 v[2:3], v[4:5], 0, s[100:101]
	s_mov_b32 m0, s46
	s_addc_u32 s11, s19, 0
	global_load_lds_dwordx4 v[2:3], off
	s_add_i32 m0, s41, 0x1c000
	v_lshl_add_u64 v[2:3], s[10:11], 0, v[0:1]
	global_load_lds_dwordx4 v[2:3], off
	v_lshl_add_u64 v[2:3], s[10:11], 0, v[130:131]
	s_add_i32 m0, s41, 0x1e000
	s_cmpk_lt_u32 s8, 0x100
	global_load_lds_dwordx4 v[2:3], off
	v_lshlrev_b32_e32 v2, 10, v10
	v_and_b32_e32 v2, 0xfffff800, v2
	v_lshl_add_u32 v2, v11, 7, v2
	v_and_b32_e32 v3, 1, v10
	v_lshl_or_b32 v2, v3, 6, v2
	v_lshl_add_u32 v136, v12, 1, v2
	v_lshlrev_b32_e32 v2, 10, v14
	v_and_b32_e32 v2, 0xfffff800, v2
	s_waitcnt vmcnt(6)
	v_lshl_add_u32 v2, v13, 7, v2
	v_and_b32_e32 v3, 1, v14
	v_lshl_or_b32 v2, v3, 6, v2
	v_readlane_b32 s10, v254, 54
	v_bitop3_b32 v143, v17, s9, v16 bitop3:0xde
	s_cselect_b64 s[8:9], -1, 0
	v_or_b32_e32 v144, s12, v18
	v_mov_b32_e32 v137, v1
	v_lshl_add_u32 v138, v15, 1, v2
	v_mov_b32_e32 v139, v1
	s_mov_b32 s47, 0
	v_add_u32_e32 v145, 0, v19
	v_readlane_b32 s26, v254, 46
	s_mov_b32 s27, s10
	s_barrier
	v_readlane_b32 s11, v254, 55
	s_branch .LBB0_276

; #define PG8_STAGE(bufoff, gbase, voff) do { _Pragma("unroll") for (int _i = 0; _i < 2; ++_i) \
;         __builtin_amdgcn_global_load_lds((const unsigned*)((const char*)(gbase) + (voff)[_i]), (PG8_LAS unsigned*)(lds + (bufoff) + ldsw + _i * 8192), 16, 0, 0); } while (0)
; #define PG8_LDA(dst, b, h) do { _Pragma("unroll") for (int m = 0; m < 4; ++m) _Pragma("unroll") for (int k = 0; k < 2; ++k) dst[m][k] = *(const PG8_LAS bf16x8*)(lds + PG8_SA(b, h) + aoff + m * 2048 + k * 1024); } while (0)
; #define PG8_LDB(dst, b, h) do { _Pragma("unroll") for (int n = 0; n < 2; ++n) _Pragma("unroll") for (int k = 0; k < 2; ++k) dst[n][k] = *(const PG8_LAS bf16x8*)(lds + PG8_SB(b, h) + boff + n * 2048 + k * 1024); } while (0)
; #define PG8_MMA(ai, bj, At, Bt) do { __builtin_amdgcn_s_setprio(1); _Pragma("unroll") for (int m = 0; m < 4; ++m) _Pragma("unroll") for (int n = 0; n < 2; ++n) _Pragma("unroll") for (int k = 0; k < 2; ++k) \
;         acc[ai][bj][m][n] = __builtin_amdgcn_mfma_f32_16x16x32_bf16(Bt[n][k], At[m][k], acc[ai][bj][m][n], 0, 0, 0); __builtin_amdgcn_s_setprio(0); } while (0)
; #define PG8_WAIT_V(n) asm volatile("s_waitcnt vmcnt(" #n ")" ::: "memory")
; template <class Epi, class Sched, bool ALIGN_EPI = false, bool SP2 = false>
; __device__ __forceinline__ void gemm_phase(PG8_LAS unsigned char* lds, const Gemm g, const Sched& S, const Epi& E, int wave_s) {
;     ...
;         const bool has_next = S.next(ui + 1, nxt);
;         const char* nA = has_next ? (const char*)g.A + (size_t)nxt.pm * tstepA : cA; const char* nB = has_next ? (const char*)g.Bt + (size_t)nxt.pn * tstepB : cB;
;         for (int t = 0; t < nt; t += 2) {
;             const bool last = (t == nt - 2);
;             const char* a1 = cA + (size_t)(t + 1) * kstep;
;             const char* a2 = last ? nA : cA + (size_t)(t + 2) * kstep; const char* b2 = last ? nB : cB + (size_t)(t + 2) * kstep;
;             const char* a3 = a2 + kstep; const char* b3 = b2 + kstep;
;             if (last && has_next) S.a_ready(nxt);
;             if constexpr (Epi::HAS_MID) { if (t == nt / 2) E.mid(acc, cur, wr, wc, fr, fq); }
;             if constexpr (SP2) {
;             PG8_LDB(B0, 0, 0); PG8_LDB(B1, 0, 1); PG8_SCHED; PG8_LDA(At, 0, 0); PG8_STAGE(PG8_SA(1, 1), a1 + hstepA, voffA);
;             PG8_WAIT_V(8); PG8_WAIT_L(0); PG8_BAR; PG8_MMA(0, 0, At, B0); PG8_MMA(0, 1, At, B1); PG8_BAR; PG8_SCHED;
.LBB0_278:
	s_ashr_i32 s13, s12, 31
	s_lshl_b64 s[14:15], s[12:13], 20
	s_add_u32 s14, s2, s14
	s_addc_u32 s15, s22, s15
	s_and_b64 s[16:17], s[38:39], exec
	s_cselect_b32 s13, s15, s21
	s_cselect_b32 s33, s14, s20
	s_ashr_i32 s11, s10, 31
	s_lshl_b64 s[16:17], s[10:11], 20
	s_add_u32 s16, s36, s16
	s_addc_u32 s17, s37, s17
	s_and_b64 s[24:25], s[38:39], exec
	s_cselect_b32 s11, s17, s19
	s_cselect_b32 s48, s16, s18
	s_add_u32 s49, s18, 0x10000
	s_addc_u32 s50, s19, 0
	s_add_u32 s18, s20, 0xc000
	v_mov_b32_e32 v2, 0
	s_addc_u32 s19, s21, 0
	s_mov_b32 s51, -2
	v_mov_b32_e32 v3, v2
	v_mov_b32_e32 v4, v2
	v_mov_b32_e32 v5, v2
	v_mov_b32_e32 v10, v2
	v_mov_b32_e32 v11, v2
	v_mov_b32_e32 v12, v2
	v_mov_b32_e32 v13, v2
	v_mov_b32_e32 v18, v2
	v_mov_b32_e32 v19, v2
	v_mov_b32_e32 v20, v2
	v_mov_b32_e32 v21, v2
	v_mov_b32_e32 v26, v2
	v_mov_b32_e32 v27, v2
	v_mov_b32_e32 v28, v2
	v_mov_b32_e32 v29, v2
	v_mov_b32_e32 v34, v2
	v_mov_b32_e32 v35, v2
	v_mov_b32_e32 v36, v2
	v_mov_b32_e32 v37, v2
	v_mov_b32_e32 v42, v2
	v_mov_b32_e32 v43, v2
	v_mov_b32_e32 v44, v2
	v_mov_b32_e32 v45, v2
	v_mov_b32_e32 v50, v2
	v_mov_b32_e32 v51, v2
	v_mov_b32_e32 v52, v2
	v_mov_b32_e32 v53, v2
	v_mov_b32_e32 v58, v2
	v_mov_b32_e32 v59, v2
	v_mov_b32_e32 v60, v2
	v_mov_b32_e32 v61, v2
	v_mov_b32_e32 v6, v2
	v_mov_b32_e32 v7, v2
	v_mov_b32_e32 v8, v2
	v_mov_b32_e32 v9, v2
	v_mov_b32_e32 v14, v2
	v_mov_b32_e32 v15, v2
	v_mov_b32_e32 v16, v2
	v_mov_b32_e32 v17, v2
	v_mov_b32_e32 v22, v2
	v_mov_b32_e32 v23, v2
	v_mov_b32_e32 v24, v2
	v_mov_b32_e32 v25, v2
	v_mov_b32_e32 v30, v2
	v_mov_b32_e32 v31, v2
	v_mov_b32_e32 v32, v2
	v_mov_b32_e32 v33, v2
	v_mov_b32_e32 v38, v2
	v_mov_b32_e32 v39, v2
	v_mov_b32_e32 v40, v2
	v_mov_b32_e32 v41, v2
	v_mov_b32_e32 v46, v2
	v_mov_b32_e32 v47, v2
	v_mov_b32_e32 v48, v2
	v_mov_b32_e32 v49, v2
	v_mov_b32_e32 v54, v2
	v_mov_b32_e32 v55, v2
	v_mov_b32_e32 v56, v2
	v_mov_b32_e32 v57, v2
	v_mov_b32_e32 v62, v2
	v_mov_b32_e32 v63, v2
	v_mov_b32_e32 v64, v2
	v_mov_b32_e32 v65, v2
	v_mov_b32_e32 v66, v2
	v_mov_b32_e32 v67, v2
	v_mov_b32_e32 v68, v2
	v_mov_b32_e32 v69, v2
	v_mov_b32_e32 v74, v2
	v_mov_b32_e32 v75, v2
	v_mov_b32_e32 v76, v2
	v_mov_b32_e32 v77, v2
	v_mov_b32_e32 v82, v2
	v_mov_b32_e32 v83, v2
	v_mov_b32_e32 v84, v2
	v_mov_b32_e32 v85, v2
	v_mov_b32_e32 v90, v2
	v_mov_b32_e32 v91, v2
	v_mov_b32_e32 v92, v2
	v_mov_b32_e32 v93, v2
	v_mov_b32_e32 v98, v2
	v_mov_b32_e32 v99, v2
	v_mov_b32_e32 v100, v2
	v_mov_b32_e32 v101, v2
	v_mov_b32_e32 v106, v2
	v_mov_b32_e32 v107, v2
	v_mov_b32_e32 v108, v2
	v_mov_b32_e32 v109, v2
	v_mov_b32_e32 v114, v2
	v_mov_b32_e32 v115, v2
	v_mov_b32_e32 v116, v2
	v_mov_b32_e32 v117, v2
	v_mov_b32_e32 v122, v2
	v_mov_b32_e32 v123, v2
	v_mov_b32_e32 v124, v2
	v_mov_b32_e32 v125, v2
	v_mov_b32_e32 v70, v2
	v_mov_b32_e32 v71, v2
	v_mov_b32_e32 v72, v2
	v_mov_b32_e32 v73, v2
	v_mov_b32_e32 v78, v2
	v_mov_b32_e32 v79, v2
	v_mov_b32_e32 v80, v2
	v_mov_b32_e32 v81, v2
	v_mov_b32_e32 v86, v2
	v_mov_b32_e32 v87, v2
	v_mov_b32_e32 v88, v2
	v_mov_b32_e32 v89, v2
	v_mov_b32_e32 v94, v2
	v_mov_b32_e32 v95, v2
	v_mov_b32_e32 v96, v2
	v_mov_b32_e32 v97, v2
	v_mov_b32_e32 v102, v2
	v_mov_b32_e32 v103, v2
	v_mov_b32_e32 v104, v2
	v_mov_b32_e32 v105, v2
	v_mov_b32_e32 v110, v2
	v_mov_b32_e32 v111, v2
	v_mov_b32_e32 v112, v2
	v_mov_b32_e32 v113, v2
	v_mov_b32_e32 v118, v2
	v_mov_b32_e32 v119, v2
	v_mov_b32_e32 v120, v2
	v_mov_b32_e32 v121, v2
	v_mov_b32_e32 v126, v2
	v_mov_b32_e32 v127, v2
	v_mov_b32_e32 v128, v2
	v_mov_b32_e32 v129, v2
.LBB0_279:
	s_add_u32 s20, s18, 0x4000
	s_addc_u32 s21, s19, 0
	s_add_i32 s34, 0, 0x10000
	s_cmp_eq_u32 s51, 28
	s_cselect_b32 s25, s13, s21
	s_cselect_b32 s24, s33, s20
	v_add_u32_e32 v140, s34, v143
	s_cselect_b32 s21, s11, s50
	s_cselect_b32 s20, s48, s49
	s_add_i32 s54, 0, 0x14000
	ds_read_b128 v[146:149], v140
	ds_read_b128 v[150:153], v140 offset:1024
	ds_read_b128 v[154:157], v140 offset:2048
	ds_read_b128 v[158:161], v140 offset:3072
	v_add_u32_e32 v140, s54, v143
	ds_read_b128 v[162:165], v140
	ds_read_b128 v[166:169], v140 offset:1024
	ds_read_b128 v[176:179], v140 offset:2048
	ds_read_b128 v[180:183], v140 offset:3072
	v_lshl_add_u64 v[140:141], s[18:19], 0, v[138:139]
	s_add_i32 m0, s41, 0xc000
	ds_read_b128 v[184:187], v145
	ds_read_b128 v[188:191], v145 offset:1024
	ds_read_b128 v[192:195], v145 offset:2048
	ds_read_b128 v[196:199], v145 offset:3072
	ds_read_b128 v[208:211], v145 offset:4096
	ds_read_b128 v[212:215], v145 offset:5120
	ds_read_b128 v[216:219], v145 offset:6144
	ds_read_b128 v[220:223], v145 offset:7168
	global_load_lds_dwordx4 v[140:141], off
	v_lshl_add_u64 v[140:141], s[18:19], 0, v[136:137]
	s_add_i32 m0, s41, 0xe000
	s_nop 0
	global_load_lds_dwordx4 v[140:141], off
	s_waitcnt vmcnt(8)
	s_waitcnt lgkmcnt(0)
	s_barrier
; #define PG8_STAGE(bufoff, gbase, voff) do { _Pragma("unroll") for (int _i = 0; _i < 2; ++_i) \
;         __builtin_amdgcn_global_load_lds((const unsigned*)((const char*)(gbase) + (voff)[_i]), (PG8_LAS unsigned*)(lds + (bufoff) + ldsw + _i * 8192), 16, 0, 0); } while (0)
; #define PG8_LDA(dst, b, h) do { _Pragma("unroll") for (int m = 0; m < 4; ++m) _Pragma("unroll") for (int k = 0; k < 2; ++k) dst[m][k] = *(const PG8_LAS bf16x8*)(lds + PG8_SA(b, h) + aoff + m * 2048 + k * 1024); } while (0)
; #define PG8_MMA(ai, bj, At, Bt) do { __builtin_amdgcn_s_setprio(1); _Pragma("unroll") for (int m = 0; m < 4; ++m) _Pragma("unroll") for (int n = 0; n < 2; ++n) _Pragma("unroll") for (int k = 0; k < 2; ++k) \
;         acc[ai][bj][m][n] = __builtin_amdgcn_mfma_f32_16x16x32_bf16(Bt[n][k], At[m][k], acc[ai][bj][m][n], 0, 0, 0); __builtin_amdgcn_s_setprio(0); } while (0)
; #define PG8_WAIT_V(n) asm volatile("s_waitcnt vmcnt(" #n ")" ::: "memory")
; #define PG8_WAIT_L(n) asm volatile("s_waitcnt lgkmcnt(" #n ")" ::: "memory")
; #define PG8_BAR __builtin_amdgcn_s_barrier()
; #define PG8_SCHED __builtin_amdgcn_sched_barrier(0)
; template <class Epi, class Sched, bool ALIGN_EPI = false, bool SP2 = false>
; __device__ __forceinline__ void gemm_phase(PG8_LAS unsigned char* lds, const Gemm g, const Sched& S, const Epi& E, int wave_s) {
;     ...
;             PG8_WAIT_V(8); PG8_WAIT_L(0); PG8_BAR; PG8_MMA(0, 0, At, B0); PG8_MMA(0, 1, At, B1); PG8_BAR; PG8_SCHED;
;             PG8_LDA(At, 0, 1); PG8_STAGE(PG8_SB(0, 0), b2, voffB); PG8_STAGE(PG8_SB(0, 1), b2 + hstepB, voffB); PG8_STAGE(PG8_SA(0, 0), a2, voffA);
;             PG8_WAIT_V(8); PG8_WAIT_L(0); PG8_BAR; PG8_MMA(1, 0, At, B0); PG8_MMA(1, 1, At, B1); PG8_BAR; PG8_SCHED;
	s_setprio 1
	s_waitcnt lgkmcnt(0)
	v_mfma_f32_16x16x32_bf16 v[126:129], v[146:149], v[184:187], v[126:129]
	v_mfma_f32_16x16x32_bf16 v[118:121], v[154:157], v[184:187], v[118:121]
	v_mfma_f32_16x16x32_bf16 v[110:113], v[146:149], v[192:195], v[110:113]
	v_mfma_f32_16x16x32_bf16 v[102:105], v[154:157], v[192:195], v[102:105]
	v_mfma_f32_16x16x32_bf16 v[94:97], v[146:149], v[208:211], v[94:97]
	v_mfma_f32_16x16x32_bf16 v[86:89], v[154:157], v[208:211], v[86:89]
	v_mfma_f32_16x16x32_bf16 v[78:81], v[146:149], v[216:219], v[78:81]
	v_mfma_f32_16x16x32_bf16 v[70:73], v[154:157], v[216:219], v[70:73]
	v_mfma_f32_16x16x32_bf16 v[126:129], v[150:153], v[188:191], v[126:129]
	v_mfma_f32_16x16x32_bf16 v[118:121], v[158:161], v[188:191], v[118:121]
	v_mfma_f32_16x16x32_bf16 v[110:113], v[150:153], v[196:199], v[110:113]
	v_mfma_f32_16x16x32_bf16 v[102:105], v[158:161], v[196:199], v[102:105]
	v_mfma_f32_16x16x32_bf16 v[94:97], v[150:153], v[212:215], v[94:97]
	v_mfma_f32_16x16x32_bf16 v[86:89], v[158:161], v[212:215], v[86:89]
	v_mfma_f32_16x16x32_bf16 v[78:81], v[150:153], v[220:223], v[78:81]
	v_mfma_f32_16x16x32_bf16 v[70:73], v[158:161], v[220:223], v[70:73]
	s_setprio 0
	s_setprio 1
	v_mfma_f32_16x16x32_bf16 v[122:125], v[162:165], v[184:187], v[122:125]
	v_mfma_f32_16x16x32_bf16 v[114:117], v[176:179], v[184:187], v[114:117]
	v_mfma_f32_16x16x32_bf16 v[106:109], v[162:165], v[192:195], v[106:109]
	v_mfma_f32_16x16x32_bf16 v[98:101], v[176:179], v[192:195], v[98:101]
	v_mfma_f32_16x16x32_bf16 v[90:93], v[162:165], v[208:211], v[90:93]
	v_mfma_f32_16x16x32_bf16 v[82:85], v[176:179], v[208:211], v[82:85]
	v_mfma_f32_16x16x32_bf16 v[74:77], v[162:165], v[216:219], v[74:77]
	v_mfma_f32_16x16x32_bf16 v[66:69], v[176:179], v[216:219], v[66:69]
	v_mfma_f32_16x16x32_bf16 v[122:125], v[166:169], v[188:191], v[122:125]
	v_mfma_f32_16x16x32_bf16 v[114:117], v[180:183], v[188:191], v[114:117]
	v_mfma_f32_16x16x32_bf16 v[106:109], v[166:169], v[196:199], v[106:109]
	v_mfma_f32_16x16x32_bf16 v[98:101], v[180:183], v[196:199], v[98:101]
	v_mfma_f32_16x16x32_bf16 v[90:93], v[166:169], v[212:215], v[90:93]
	v_mfma_f32_16x16x32_bf16 v[82:85], v[180:183], v[212:215], v[82:85]
	v_mfma_f32_16x16x32_bf16 v[74:77], v[166:169], v[220:223], v[74:77]
	v_mfma_f32_16x16x32_bf16 v[66:69], v[180:183], v[220:223], v[66:69]
	s_setprio 0
	s_barrier
	s_add_i32 s34, s34, s40
	v_lshl_add_u64 v[140:141], s[20:21], 0, v[0:1]
	s_mov_b32 m0, s34
	ds_read_b128 v[184:187], v145 offset:16384
	ds_read_b128 v[188:191], v145 offset:17408
	ds_read_b128 v[192:195], v145 offset:18432
	ds_read_b128 v[196:199], v145 offset:19456
	ds_read_b128 v[208:211], v145 offset:20480
	ds_read_b128 v[212:215], v145 offset:21504
	ds_read_b128 v[216:219], v145 offset:22528
	ds_read_b128 v[220:223], v145 offset:23552
	global_load_lds_dwordx4 v[140:141], off
	s_add_i32 m0, s34, 0x2000
	s_add_u32 s34, s20, 0x4000
	v_lshl_add_u64 v[170:171], s[20:21], 0, v[130:131]
	s_addc_u32 s35, s21, 0
	s_add_i32 s54, s54, s40
	global_load_lds_dwordx4 v[170:171], off
	v_lshl_add_u64 v[200:201], s[34:35], 0, v[0:1]
	s_mov_b32 m0, s54
	v_lshl_add_u64 v[224:225], s[24:25], 0, v[132:133]
	global_load_lds_dwordx4 v[200:201], off
	v_lshl_add_u64 v[200:201], s[34:35], 0, v[130:131]
	s_add_i32 m0, s54, 0x2000
	s_nop 0
	global_load_lds_dwordx4 v[200:201], off
	v_lshl_add_u64 v[200:201], s[24:25], 0, v[134:135]
	s_mov_b32 m0, s41
	s_nop 0
	global_load_lds_dwordx4 v[200:201], off
	s_mov_b32 m0, s42
	s_nop 0
	global_load_lds_dwordx4 v[224:225], off
	s_waitcnt vmcnt(8)
	s_waitcnt lgkmcnt(0)
	s_barrier
	s_setprio 1
	s_waitcnt lgkmcnt(0)
	v_mfma_f32_16x16x32_bf16 v[62:65], v[146:149], v[184:187], v[62:65]
	v_mfma_f32_16x16x32_bf16 v[54:57], v[154:157], v[184:187], v[54:57]
	v_mfma_f32_16x16x32_bf16 v[46:49], v[146:149], v[192:195], v[46:49]
	v_mfma_f32_16x16x32_bf16 v[38:41], v[154:157], v[192:195], v[38:41]
	v_mfma_f32_16x16x32_bf16 v[30:33], v[146:149], v[208:211], v[30:33]
	v_mfma_f32_16x16x32_bf16 v[22:25], v[154:157], v[208:211], v[22:25]
	v_mfma_f32_16x16x32_bf16 v[14:17], v[146:149], v[216:219], v[14:17]
	v_mfma_f32_16x16x32_bf16 v[6:9], v[154:157], v[216:219], v[6:9]
	v_mfma_f32_16x16x32_bf16 v[62:65], v[150:153], v[188:191], v[62:65]
	v_mfma_f32_16x16x32_bf16 v[54:57], v[158:161], v[188:191], v[54:57]
	v_mfma_f32_16x16x32_bf16 v[46:49], v[150:153], v[196:199], v[46:49]
	v_mfma_f32_16x16x32_bf16 v[38:41], v[158:161], v[196:199], v[38:41]
	v_mfma_f32_16x16x32_bf16 v[30:33], v[150:153], v[212:215], v[30:33]
	v_mfma_f32_16x16x32_bf16 v[22:25], v[158:161], v[212:215], v[22:25]
	v_mfma_f32_16x16x32_bf16 v[14:17], v[150:153], v[220:223], v[14:17]
	v_mfma_f32_16x16x32_bf16 v[6:9], v[158:161], v[220:223], v[6:9]
	s_setprio 0
	s_setprio 1
	v_mfma_f32_16x16x32_bf16 v[58:61], v[162:165], v[184:187], v[58:61]
	v_mfma_f32_16x16x32_bf16 v[50:53], v[176:179], v[184:187], v[50:53]
	v_mfma_f32_16x16x32_bf16 v[42:45], v[162:165], v[192:195], v[42:45]
	v_mfma_f32_16x16x32_bf16 v[34:37], v[176:179], v[192:195], v[34:37]
	v_mfma_f32_16x16x32_bf16 v[26:29], v[162:165], v[208:211], v[26:29]
	v_mfma_f32_16x16x32_bf16 v[18:21], v[176:179], v[208:211], v[18:21]
	v_mfma_f32_16x16x32_bf16 v[10:13], v[162:165], v[216:219], v[10:13]
	v_mfma_f32_16x16x32_bf16 v[2:5], v[176:179], v[216:219], v[2:5]
	v_mfma_f32_16x16x32_bf16 v[58:61], v[166:169], v[188:191], v[58:61]
	v_mfma_f32_16x16x32_bf16 v[50:53], v[180:183], v[188:191], v[50:53]
	v_mfma_f32_16x16x32_bf16 v[42:45], v[166:169], v[196:199], v[42:45]
	v_mfma_f32_16x16x32_bf16 v[34:37], v[180:183], v[196:199], v[34:37]
	v_mfma_f32_16x16x32_bf16 v[26:29], v[166:169], v[212:215], v[26:29]
	v_mfma_f32_16x16x32_bf16 v[18:21], v[180:183], v[212:215], v[18:21]
	v_mfma_f32_16x16x32_bf16 v[10:13], v[166:169], v[220:223], v[10:13]
	v_mfma_f32_16x16x32_bf16 v[2:5], v[180:183], v[220:223], v[2:5]
	s_setprio 0
	s_barrier
; #define PG8_STAGE(bufoff, gbase, voff) do { _Pragma("unroll") for (int _i = 0; _i < 2; ++_i) \
;         __builtin_amdgcn_global_load_lds((const unsigned*)((const char*)(gbase) + (voff)[_i]), (PG8_LAS unsigned*)(lds + (bufoff) + ldsw + _i * 8192), 16, 0, 0); } while (0)
; #define PG8_LDA(dst, b, h) do { _Pragma("unroll") for (int m = 0; m < 4; ++m) _Pragma("unroll") for (int k = 0; k < 2; ++k) dst[m][k] = *(const PG8_LAS bf16x8*)(lds + PG8_SA(b, h) + aoff + m * 2048 + k * 1024); } while (0)
; #define PG8_LDB(dst, b, h) do { _Pragma("unroll") for (int n = 0; n < 2; ++n) _Pragma("unroll") for (int k = 0; k < 2; ++k) dst[n][k] = *(const PG8_LAS bf16x8*)(lds + PG8_SB(b, h) + boff + n * 2048 + k * 1024); } while (0)
; #define PG8_MMA(ai, bj, At, Bt) do { __builtin_amdgcn_s_setprio(1); _Pragma("unroll") for (int m = 0; m < 4; ++m) _Pragma("unroll") for (int n = 0; n < 2; ++n) _Pragma("unroll") for (int k = 0; k < 2; ++k) \
;         acc[ai][bj][m][n] = __builtin_amdgcn_mfma_f32_16x16x32_bf16(Bt[n][k], At[m][k], acc[ai][bj][m][n], 0, 0, 0); __builtin_amdgcn_s_setprio(0); } while (0)
; #define PG8_WAIT_V(n) asm volatile("s_waitcnt vmcnt(" #n ")" ::: "memory")
; #define PG8_WAIT_L(n) asm volatile("s_waitcnt lgkmcnt(" #n ")" ::: "memory")
; #define PG8_BAR __builtin_amdgcn_s_barrier()
; #define PG8_SCHED __builtin_amdgcn_sched_barrier(0)
; template <class Epi, class Sched, bool ALIGN_EPI = false, bool SP2 = false>
; __device__ __forceinline__ void gemm_phase(PG8_LAS unsigned char* lds, const Gemm g, const Sched& S, const Epi& E, int wave_s) {
;     ...
;             PG8_LDB(B0, 1, 0); PG8_LDB(B1, 1, 1); PG8_SCHED; PG8_LDA(At, 1, 0); PG8_STAGE(PG8_SA(0, 1), a2 + hstepA, voffA);
;             PG8_WAIT_V(8); PG8_WAIT_L(0); PG8_BAR; PG8_MMA(0, 0, At, B0); PG8_MMA(0, 1, At, B1); PG8_BAR; PG8_SCHED;
	s_add_i32 s34, 0, 0x18000
	s_add_i32 s35, 0, 0x1c000
	v_add_u32_e32 v158, s34, v143
	v_add_u32_e32 v180, s35, v143
	ds_read_b128 v[146:149], v158
	ds_read_b128 v[150:153], v158 offset:1024
	ds_read_b128 v[154:157], v158 offset:2048
	ds_read_b128 v[158:161], v158 offset:3072
	ds_read_b128 v[162:165], v180
	ds_read_b128 v[166:169], v180 offset:1024
	ds_read_b128 v[176:179], v180 offset:2048
	ds_read_b128 v[180:183], v180 offset:3072
	s_add_u32 s24, s24, 0x4000
	s_addc_u32 s25, s25, 0
	s_mov_b32 m0, s43
	v_lshl_add_u64 v[226:227], s[24:25], 0, v[134:135]
	ds_read_b128 v[184:187], v145 offset:32768
	ds_read_b128 v[188:191], v145 offset:33792
	ds_read_b128 v[192:195], v145 offset:34816
	ds_read_b128 v[196:199], v145 offset:35840
	ds_read_b128 v[208:211], v145 offset:36864
	ds_read_b128 v[212:215], v145 offset:37888
	ds_read_b128 v[216:219], v145 offset:38912
	ds_read_b128 v[220:223], v145 offset:39936
	global_load_lds_dwordx4 v[226:227], off
	v_lshl_add_u64 v[226:227], s[24:25], 0, v[132:133]
	s_mov_b32 m0, s44
	s_nop 0
	global_load_lds_dwordx4 v[226:227], off
	s_waitcnt vmcnt(8)
	s_waitcnt lgkmcnt(0)
	s_barrier
	s_setprio 1
	s_waitcnt lgkmcnt(0)
	v_mfma_f32_16x16x32_bf16 v[126:129], v[146:149], v[184:187], v[126:129]
	v_mfma_f32_16x16x32_bf16 v[118:121], v[154:157], v[184:187], v[118:121]
	v_mfma_f32_16x16x32_bf16 v[110:113], v[146:149], v[192:195], v[110:113]
	v_mfma_f32_16x16x32_bf16 v[102:105], v[154:157], v[192:195], v[102:105]
	v_mfma_f32_16x16x32_bf16 v[94:97], v[146:149], v[208:211], v[94:97]
	v_mfma_f32_16x16x32_bf16 v[86:89], v[154:157], v[208:211], v[86:89]
	v_mfma_f32_16x16x32_bf16 v[78:81], v[146:149], v[216:219], v[78:81]
	v_mfma_f32_16x16x32_bf16 v[70:73], v[154:157], v[216:219], v[70:73]
	v_mfma_f32_16x16x32_bf16 v[126:129], v[150:153], v[188:191], v[126:129]
	v_mfma_f32_16x16x32_bf16 v[118:121], v[158:161], v[188:191], v[118:121]
	v_mfma_f32_16x16x32_bf16 v[110:113], v[150:153], v[196:199], v[110:113]
	v_mfma_f32_16x16x32_bf16 v[102:105], v[158:161], v[196:199], v[102:105]
	v_mfma_f32_16x16x32_bf16 v[94:97], v[150:153], v[212:215], v[94:97]
	v_mfma_f32_16x16x32_bf16 v[86:89], v[158:161], v[212:215], v[86:89]
	v_mfma_f32_16x16x32_bf16 v[78:81], v[150:153], v[220:223], v[78:81]
	v_mfma_f32_16x16x32_bf16 v[70:73], v[158:161], v[220:223], v[70:73]
	s_setprio 0
	s_setprio 1
	v_mfma_f32_16x16x32_bf16 v[122:125], v[162:165], v[184:187], v[122:125]
	v_mfma_f32_16x16x32_bf16 v[114:117], v[176:179], v[184:187], v[114:117]
	v_mfma_f32_16x16x32_bf16 v[106:109], v[162:165], v[192:195], v[106:109]
	v_mfma_f32_16x16x32_bf16 v[98:101], v[176:179], v[192:195], v[98:101]
	v_mfma_f32_16x16x32_bf16 v[90:93], v[162:165], v[208:211], v[90:93]
	v_mfma_f32_16x16x32_bf16 v[82:85], v[176:179], v[208:211], v[82:85]
	v_mfma_f32_16x16x32_bf16 v[74:77], v[162:165], v[216:219], v[74:77]
	v_mfma_f32_16x16x32_bf16 v[66:69], v[176:179], v[216:219], v[66:69]
	v_mfma_f32_16x16x32_bf16 v[122:125], v[166:169], v[188:191], v[122:125]
	v_mfma_f32_16x16x32_bf16 v[114:117], v[180:183], v[188:191], v[114:117]
	v_mfma_f32_16x16x32_bf16 v[106:109], v[166:169], v[196:199], v[106:109]
	v_mfma_f32_16x16x32_bf16 v[98:101], v[180:183], v[196:199], v[98:101]
	v_mfma_f32_16x16x32_bf16 v[90:93], v[166:169], v[212:215], v[90:93]
	v_mfma_f32_16x16x32_bf16 v[82:85], v[180:183], v[212:215], v[82:85]
	v_mfma_f32_16x16x32_bf16 v[74:77], v[166:169], v[220:223], v[74:77]
	v_mfma_f32_16x16x32_bf16 v[66:69], v[180:183], v[220:223], v[66:69]
	s_setprio 0
	s_barrier
; #define PG8_STAGE(bufoff, gbase, voff) do { _Pragma("unroll") for (int _i = 0; _i < 2; ++_i) \
;         __builtin_amdgcn_global_load_lds((const unsigned*)((const char*)(gbase) + (voff)[_i]), (PG8_LAS unsigned*)(lds + (bufoff) + ldsw + _i * 8192), 16, 0, 0); } while (0)
; #define PG8_LDA(dst, b, h) do { _Pragma("unroll") for (int m = 0; m < 4; ++m) _Pragma("unroll") for (int k = 0; k < 2; ++k) dst[m][k] = *(const PG8_LAS bf16x8*)(lds + PG8_SA(b, h) + aoff + m * 2048 + k * 1024); } while (0)
; #define PG8_WAIT_V(n) asm volatile("s_waitcnt vmcnt(" #n ")" ::: "memory")
; #define PG8_BAR __builtin_amdgcn_s_barrier()
; template <class Epi, class Sched, bool ALIGN_EPI = false, bool SP2 = false>
; __device__ __forceinline__ void gemm_phase(PG8_LAS unsigned char* lds, const Gemm g, const Sched& S, const Epi& E, int wave_s) {
;     ...
;         for (int t = 0; t < nt; t += 2) {
;             const bool last = (t == nt - 2);
;             const char* a1 = cA + (size_t)(t + 1) * kstep;
;             const char* a2 = last ? nA : cA + (size_t)(t + 2) * kstep; const char* b2 = last ? nB : cB + (size_t)(t + 2) * kstep;
;             const char* a3 = a2 + kstep; const char* b3 = b2 + kstep;
;             if (last && has_next) S.a_ready(nxt);
;             if constexpr (Epi::HAS_MID) { if (t == nt / 2) E.mid(acc, cur, wr, wc, fr, fq); }
;             if constexpr (SP2) {
;             PG8_LDB(B0, 0, 0); PG8_LDB(B1, 0, 1); PG8_SCHED; PG8_LDA(At, 0, 0); PG8_STAGE(PG8_SA(1, 1), a1 + hstepA, voffA);
;             PG8_WAIT_V(8); PG8_WAIT_L(0); PG8_BAR; PG8_MMA(0, 0, At, B0); PG8_MMA(0, 1, At, B1); PG8_BAR; PG8_SCHED;
;             PG8_LDA(At, 0, 1); PG8_STAGE(PG8_SB(0, 0), b2, voffB); PG8_STAGE(PG8_SB(0, 1), b2 + hstepB, voffB); PG8_STAGE(PG8_SA(0, 0), a2, voffA);
;             PG8_WAIT_V(8); PG8_WAIT_L(0); PG8_BAR; PG8_MMA(1, 0, At, B0); PG8_MMA(1, 1, At, B1); PG8_BAR; PG8_SCHED;
;             PG8_LDB(B0, 1, 0); PG8_LDB(B1, 1, 1); PG8_SCHED; PG8_LDA(At, 1, 0); PG8_STAGE(PG8_SA(0, 1), a2 + hstepA, voffA);
;             PG8_WAIT_V(8); PG8_WAIT_L(0); PG8_BAR; PG8_MMA(0, 0, At, B0); PG8_MMA(0, 1, At, B1); PG8_BAR; PG8_SCHED;
;             PG8_LDA(At, 1, 1); PG8_STAGE(PG8_SB(1, 0), b3, voffB); PG8_STAGE(PG8_SB(1, 1), b3 + hstepB, voffB); PG8_STAGE(PG8_SA(1, 0), a3, voffA);
;             PG8_WAIT_V(8); PG8_WAIT_L(0); PG8_BAR; PG8_MMA(1, 0, At, B0); PG8_MMA(1, 1, At, B1); PG8_BAR; PG8_SCHED;
	s_add_i32 s24, s34, s40
	s_mov_b64 s[100:101], 0x8000
	v_lshl_add_u64 v[140:141], v[140:141], 0, s[100:101]
	s_mov_b32 m0, s24
	ds_read_b128 v[184:187], v145 offset:49152
	ds_read_b128 v[188:191], v145 offset:50176
	ds_read_b128 v[192:195], v145 offset:51200
	ds_read_b128 v[196:199], v145 offset:52224
	ds_read_b128 v[208:211], v145 offset:53248
	ds_read_b128 v[212:215], v145 offset:54272
	ds_read_b128 v[216:219], v145 offset:55296
	ds_read_b128 v[220:223], v145 offset:56320
	global_load_lds_dwordx4 v[140:141], off
	s_add_i32 m0, s24, 0x2000
	s_add_u32 s20, s20, 0xc000
	v_lshl_add_u64 v[140:141], v[170:171], 0, s[100:101]
	s_addc_u32 s21, s21, 0
	s_add_i32 s24, s35, s40
	global_load_lds_dwordx4 v[140:141], off
	v_lshl_add_u64 v[140:141], s[20:21], 0, v[0:1]
	s_mov_b32 m0, s24
	s_nop 0
	global_load_lds_dwordx4 v[140:141], off
	v_lshl_add_u64 v[140:141], s[20:21], 0, v[130:131]
	s_add_i32 m0, s24, 0x2000
	s_nop 0
	global_load_lds_dwordx4 v[140:141], off
	s_mov_b64 s[100:101], 0x8000
	v_lshl_add_u64 v[140:141], v[200:201], 0, s[100:101]
	s_mov_b32 m0, s45
	s_nop 0
	global_load_lds_dwordx4 v[140:141], off
	v_lshl_add_u64 v[140:141], v[224:225], 0, s[100:101]
	s_mov_b32 m0, s46
	s_nop 0
	global_load_lds_dwordx4 v[140:141], off
	s_waitcnt vmcnt(8)
	s_waitcnt lgkmcnt(0)
	s_barrier
	s_setprio 1
	s_waitcnt lgkmcnt(0)
	v_mfma_f32_16x16x32_bf16 v[62:65], v[146:149], v[184:187], v[62:65]
	v_mfma_f32_16x16x32_bf16 v[54:57], v[154:157], v[184:187], v[54:57]
	v_mfma_f32_16x16x32_bf16 v[46:49], v[146:149], v[192:195], v[46:49]
	v_mfma_f32_16x16x32_bf16 v[38:41], v[154:157], v[192:195], v[38:41]
	v_mfma_f32_16x16x32_bf16 v[30:33], v[146:149], v[208:211], v[30:33]
	v_mfma_f32_16x16x32_bf16 v[22:25], v[154:157], v[208:211], v[22:25]
	v_mfma_f32_16x16x32_bf16 v[14:17], v[146:149], v[216:219], v[14:17]
	v_mfma_f32_16x16x32_bf16 v[6:9], v[154:157], v[216:219], v[6:9]
	v_mfma_f32_16x16x32_bf16 v[62:65], v[150:153], v[188:191], v[62:65]
	v_mfma_f32_16x16x32_bf16 v[54:57], v[158:161], v[188:191], v[54:57]
	v_mfma_f32_16x16x32_bf16 v[46:49], v[150:153], v[196:199], v[46:49]
	v_mfma_f32_16x16x32_bf16 v[38:41], v[158:161], v[196:199], v[38:41]
	v_mfma_f32_16x16x32_bf16 v[30:33], v[150:153], v[212:215], v[30:33]
	v_mfma_f32_16x16x32_bf16 v[22:25], v[158:161], v[212:215], v[22:25]
	v_mfma_f32_16x16x32_bf16 v[14:17], v[150:153], v[220:223], v[14:17]
	v_mfma_f32_16x16x32_bf16 v[6:9], v[158:161], v[220:223], v[6:9]
	s_setprio 0
	s_setprio 1
	v_mfma_f32_16x16x32_bf16 v[58:61], v[162:165], v[184:187], v[58:61]
	v_mfma_f32_16x16x32_bf16 v[50:53], v[176:179], v[184:187], v[50:53]
	v_mfma_f32_16x16x32_bf16 v[42:45], v[162:165], v[192:195], v[42:45]
	v_mfma_f32_16x16x32_bf16 v[34:37], v[176:179], v[192:195], v[34:37]
	v_mfma_f32_16x16x32_bf16 v[26:29], v[162:165], v[208:211], v[26:29]
	v_mfma_f32_16x16x32_bf16 v[18:21], v[176:179], v[208:211], v[18:21]
	v_mfma_f32_16x16x32_bf16 v[10:13], v[162:165], v[216:219], v[10:13]
	v_mfma_f32_16x16x32_bf16 v[2:5], v[176:179], v[216:219], v[2:5]
	v_mfma_f32_16x16x32_bf16 v[58:61], v[166:169], v[188:191], v[58:61]
	v_mfma_f32_16x16x32_bf16 v[50:53], v[180:183], v[188:191], v[50:53]
	v_mfma_f32_16x16x32_bf16 v[42:45], v[166:169], v[196:199], v[42:45]
	v_mfma_f32_16x16x32_bf16 v[34:37], v[180:183], v[196:199], v[34:37]
	v_mfma_f32_16x16x32_bf16 v[26:29], v[166:169], v[212:215], v[26:29]
	v_mfma_f32_16x16x32_bf16 v[18:21], v[180:183], v[212:215], v[18:21]
	v_mfma_f32_16x16x32_bf16 v[10:13], v[166:169], v[220:223], v[10:13]
	v_mfma_f32_16x16x32_bf16 v[2:5], v[180:183], v[220:223], v[2:5]
	s_setprio 0
	s_barrier
	s_add_i32 s51, s51, 2
	s_add_u32 s49, s49, 0x10000
	s_addc_u32 s50, s50, 0
	s_add_u32 s18, s18, 0x10000
	s_addc_u32 s19, s19, 0
	s_cmp_gt_u32 s51, 29
	s_cbranch_scc0 .LBB0_279
	s_and_b64 vcc, exec, s[8:9]
	s_cbranch_vccz .LBB0_282
	s_barrier

; #define GAS __attribute__((address_space(1)))
; __device__ __forceinline__ void modulate_phase(Frame& F, const float* x, bf16* H, const float* gnorm, const float* modsub) {
;     const int gw = F.vcu * NWAVES + F.wave, NGW = F.G * NWAVES, per = (M + NGW - 1) / NGW;
;     const int rbeg = gw * per, rend = min(rbeg + per, M);
;     if (rbeg >= rend) return;
;     f32x4 gs[8], sh[8]; int curb = -1;
;     f32x4 v[8], nv[8];
;     { const GAS f32x4* xr = (const GAS f32x4*)(x + (size_t)rbeg * D) + F.lane;
; #pragma unroll
;       for (int j = 0; j < 8; ++j) v[j] = xr[64 * j]; }
; #pragma unroll 1
;     for (int r = rbeg; r < rend; ++r) {
;         { const GAS f32x4* xn = (const GAS f32x4*)(x + (size_t)min(r + 1, rend - 1) * D) + F.lane;
; #pragma unroll
;           for (int j = 0; j < 8; ++j) nv[j] = xn[64 * j]; }
;         const int b = r >> 12;
;         if (b != curb) { curb = b;
; #pragma unroll
;             for (int j = 0; j < 8; ++j) { const int c = 4 * F.lane + 256 * j;
;                 const f32x4 g = *(const GAS f32x4*)(gnorm + c), sc = *(const GAS f32x4*)(modsub + (size_t)b * NMOD + D + c);
;                 gs[j] = g * (sc + 1.0f); sh[j] = *(const GAS f32x4*)(modsub + (size_t)b * NMOD + c); } }
;         float s = 0.f;
; #pragma unroll
;         for (int j = 0; j < 8; ++j) s += (v[j].x * v[j].x + v[j].y * v[j].y) + (v[j].z * v[j].z + v[j].w * v[j].w);
.LBB0_1731:
	s_andn2_b64 vcc, exec, s[0:1]
	s_cbranch_vccnz .LBB0_1785
	s_load_dwordx2 s[6:7], s[82:83], 0xb8
	v_mov_b32_e32 v0, v1
	s_waitcnt lgkmcnt(0)
	v_readlane_b32 s0, v253, 21
	v_mbcnt_lo_u32_b32 v0, -1, v0
	v_mbcnt_hi_u32_b32 v0, -1, v0
	v_or_b32_e32 v0, s0, v0
	v_readlane_b32 s1, v255, 0
	v_readfirstlane_b32 s0, v0
	s_ashr_i32 s0, s0, 6
	s_add_i32 s0, s0, s74
	s_mul_i32 s0, s1, s0
	s_add_i32 s1, s0, s1
	v_readlane_b32 s8, v255, 42
	s_min_i32 s2, s1, 0x4000
	v_readlane_b32 s9, v255, 43
	s_cmp_ge_i32 s0, s2
	s_cbranch_scc1 .LBB0_1737
	s_add_u32 s12, s6, 0x16d90000
	s_addc_u32 s13, s7, 0
	s_mul_i32 s1, s78, 0x48000
	s_add_u32 s1, s6, s1
	s_addc_u32 s10, s7, 0
	s_add_u32 s14, s1, 0x10c000
	s_addc_u32 s15, s10, 0
	s_mul_i32 s1, s78, 0x6000
	s_add_u32 s1, s8, s1
	s_addc_u32 s8, s9, 0
	s_add_u32 s10, s1, 0x4000
	s_addc_u32 s11, s8, 0
	s_ashr_i32 s1, s0, 31
	s_lshl_b64 s[8:9], s[0:1], 13
	s_waitcnt vmcnt(0)
	v_and_b32_e32 v130, 63, v0
	s_add_u32 s8, s12, s8
	s_addc_u32 s9, s13, s9
	v_lshlrev_b32_e32 v0, 4, v130
	v_lshl_add_u64 v[2:3], s[8:9], 0, v[0:1]
	global_load_dwordx4 v[94:97], v0, s[8:9]
	global_load_dwordx4 v[82:85], v0, s[8:9] offset:1024
	global_load_dwordx4 v[46:49], v0, s[8:9] offset:2048
	global_load_dwordx4 v[34:37], v0, s[8:9] offset:3072
	s_movk_i32 s8, 0x1000
	v_add_co_u32_e32 v2, vcc, s8, v2
	v_lshlrev_b32_e32 v6, 2, v130
	s_nop 0
	v_addc_co_u32_e32 v3, vcc, 0, v3, vcc
	global_load_dwordx4 v[30:33], v[2:3], off
	global_load_dwordx4 v[18:21], v[2:3], off offset:1024
	global_load_dwordx4 v[14:17], v[2:3], off offset:2048
	s_nop 0
	global_load_dwordx4 v[2:5], v[2:3], off offset:3072
	v_or_b32_e32 v8, 0x100, v6
	v_or_b32_e32 v10, 0x200, v6
	v_lshl_add_u64 v[132:133], s[10:11], 0, v[0:1]
	v_lshlrev_b32_e32 v0, 2, v8
	v_or_b32_e32 v12, 0x300, v6
	v_lshl_add_u64 v[134:135], s[10:11], 0, v[0:1]
	v_lshlrev_b32_e32 v0, 2, v10
	v_or_b32_e32 v22, 0x400, v6
	v_lshl_add_u64 v[136:137], s[10:11], 0, v[0:1]
	v_lshlrev_b32_e32 v0, 2, v12
	v_or_b32_e32 v24, 0x500, v6
	v_lshl_add_u64 v[138:139], s[10:11], 0, v[0:1]
	v_lshlrev_b32_e32 v0, 2, v22
	v_or_b32_e32 v26, 0x600, v6
	v_lshl_add_u64 v[140:141], s[10:11], 0, v[0:1]
	v_lshlrev_b32_e32 v0, 2, v24
	v_or_b32_e32 v28, 0x700, v6
	v_lshl_add_u64 v[142:143], s[10:11], 0, v[0:1]
	v_lshlrev_b32_e32 v0, 2, v26
	v_lshl_add_u64 v[144:145], s[10:11], 0, v[0:1]
	v_lshlrev_b32_e32 v0, 2, v28
	s_add_i32 s16, s2, -1
	v_lshl_add_u64 v[146:147], s[10:11], 0, v[0:1]
	s_lshr_b32 s10, s0, 8
	s_lshl_b32 s10, s10, 20
	s_and_b32 s11, s0, 0xff
	s_lshl_b32 s11, s11, 7
	s_add_u32 s10, s10, s11
	s_mov_b32 s11, 0
	s_add_u32 s1, s6, s10
	s_addc_u32 s7, s7, s11
	s_add_u32 s6, s1, 0x1ed90000
	s_mov_b32 s8, -1
	s_addc_u32 s7, s7, 0
	v_lshlrev_b32_e32 v131, 2, v6
	v_lshlrev_b32_e32 v148, 2, v8
	v_lshlrev_b32_e32 v149, 2, v10
	v_lshlrev_b32_e32 v150, 2, v12
	v_lshlrev_b32_e32 v151, 2, v22
	v_lshlrev_b32_e32 v152, 2, v24
	v_lshlrev_b32_e32 v153, 2, v26
	v_lshlrev_b32_e32 v154, 2, v28
	s_branch .LBB0_1735
.LBB0_1734:
	s_waitcnt vmcnt(15)
	v_mul_f32_e32 v0, v95, v95
	v_mul_f32_e32 v155, v97, v97
	v_fmac_f32_e32 v0, v94, v94
	v_fmac_f32_e32 v155, v96, v96
	v_add_f32_e32 v0, v0, v155
	s_waitcnt vmcnt(14)
	v_mul_f32_e32 v155, v83, v83
	v_mul_f32_e32 v156, v85, v85
	v_fmac_f32_e32 v155, v82, v82
	v_fmac_f32_e32 v156, v84, v84
	v_add_f32_e32 v155, v155, v156
	v_add_f32_e32 v0, v0, v155
	s_waitcnt vmcnt(13)
	v_mul_f32_e32 v155, v47, v47
	v_mul_f32_e32 v156, v49, v49
	v_fmac_f32_e32 v155, v46, v46
	v_fmac_f32_e32 v156, v48, v48
	v_add_f32_e32 v155, v155, v156
	v_add_f32_e32 v0, v155, v0
	s_waitcnt vmcnt(12)
	v_mul_f32_e32 v155, v35, v35
	v_mul_f32_e32 v156, v37, v37
	v_fmac_f32_e32 v155, v34, v34
	v_fmac_f32_e32 v156, v36, v36
	v_add_f32_e32 v155, v155, v156
	v_add_f32_e32 v0, v155, v0
	s_waitcnt vmcnt(11)
	v_mul_f32_e32 v155, v31, v31
	v_mul_f32_e32 v156, v33, v33
	v_fmac_f32_e32 v155, v30, v30
	v_fmac_f32_e32 v156, v32, v32
	v_add_f32_e32 v155, v155, v156
	v_add_f32_e32 v0, v155, v0
	s_waitcnt vmcnt(10)
	v_mul_f32_e32 v155, v19, v19
	v_mul_f32_e32 v156, v21, v21
	v_fmac_f32_e32 v155, v18, v18
	v_fmac_f32_e32 v156, v20, v20
	v_add_f32_e32 v155, v155, v156
	v_add_f32_e32 v0, v155, v0
	s_waitcnt vmcnt(9)
	v_mul_f32_e32 v155, v15, v15
	v_mul_f32_e32 v156, v17, v17
	v_fmac_f32_e32 v155, v14, v14
	v_fmac_f32_e32 v156, v16, v16
	v_add_f32_e32 v155, v155, v156
	v_add_f32_e32 v0, v155, v0
	s_waitcnt vmcnt(8)
	v_mul_f32_e32 v155, v3, v3
	v_mul_f32_e32 v156, v5, v5
	v_fmac_f32_e32 v155, v2, v2
	v_fmac_f32_e32 v156, v4, v4
	v_add_f32_e32 v155, v155, v156
	v_add_f32_e32 v0, v155, v0
	ds_swizzle_b32 v155, v0 offset:swizzle(SWAP,1)
	s_waitcnt lgkmcnt(0)
	v_add_f32_e32 v0, v0, v155
	ds_swizzle_b32 v155, v0 offset:swizzle(SWAP,2)
	s_waitcnt lgkmcnt(0)
	v_add_f32_e32 v0, v0, v155
	ds_swizzle_b32 v155, v0 offset:swizzle(SWAP,4)
	s_waitcnt lgkmcnt(0)
	v_add_f32_e32 v0, v0, v155
	ds_swizzle_b32 v155, v0 offset:swizzle(SWAP,8)
	s_waitcnt lgkmcnt(0)
	v_add_f32_e32 v0, v0, v155
	ds_swizzle_b32 v155, v0 offset:swizzle(SWAP,16)
	s_waitcnt lgkmcnt(0)
; #define GAS __attribute__((address_space(1)))
; __device__ __forceinline__ unsigned pk2(float lo, float hi) { return f2bf(lo) | (f2bf(hi) << 16); }
; __device__ __forceinline__ void modulate_phase(Frame& F, const float* x, bf16* H, const float* gnorm, const float* modsub) {
;     ...
;         const float rstd = 1.0f / sqrtf(wave_sum(s) * (1.0f / D) + RMS_EPS);
;         GAS unsigned long long* o8 = (GAS unsigned long long*)(H + (size_t)r * D) + F.lane;
; #pragma unroll
;         for (int j = 0; j < 8; ++j) { const f32x4 y = v[j] * rstd * gs[j] + sh[j];
;             o8[64 * j] = (unsigned long long)pk2(y.x, y.y) | ((unsigned long long)pk2(y.z, y.w) << 32); }
	v_add_f32_e32 v0, v0, v155
	v_mov_b32_e32 v155, v0
	s_nop 1
	v_permlane32_swap_b32_e32 v0, v155
	v_add_f32_e32 v0, v0, v155
	v_fmamk_f32 v0, v0, 0x3a000000, v202
	v_mul_f32_e32 v155, 0x4f800000, v0
	v_cmp_gt_f32_e32 vcc, s60, v0
	s_nop 1
	v_cndmask_b32_e32 v0, v0, v155, vcc
	v_sqrt_f32_e32 v155, v0
	s_nop 0
	v_add_u32_e32 v156, -1, v155
	v_fma_f32 v157, -v156, v155, v0
	v_cmp_ge_f32_e64 s[40:41], 0, v157
	v_add_u32_e32 v157, 1, v155
	s_nop 0
	v_cndmask_b32_e64 v156, v155, v156, s[40:41]
	v_fma_f32 v155, -v157, v155, v0
	v_cmp_lt_f32_e64 s[40:41], 0, v155
	s_nop 1
	v_cndmask_b32_e64 v155, v156, v157, s[40:41]
	v_mul_f32_e32 v156, 0x37800000, v155
	v_cndmask_b32_e32 v155, v155, v156, vcc
	v_cmp_class_f32_e32 vcc, v0, v203
	s_nop 1
	v_cndmask_b32_e32 v0, v155, v0, vcc
	v_div_scale_f32 v155, s[10:11], v0, v0, 1.0
	v_rcp_f32_e32 v156, v155
	s_nop 0
	v_fma_f32 v157, -v155, v156, 1.0
	v_fmac_f32_e32 v156, v157, v156
	v_div_scale_f32 v157, vcc, 1.0, v0, 1.0
	v_mul_f32_e32 v158, v157, v156
	v_fma_f32 v159, -v155, v158, v157
	v_fmac_f32_e32 v158, v159, v156
	v_fma_f32 v155, -v155, v158, v157
	v_div_fmas_f32 v155, v155, v156, v158
	v_div_fixup_f32 v0, v155, v0, 1.0
	v_pk_mul_f32 v[94:95], v[94:95], v[0:1] op_sel_hi:[1,0]
	v_pk_mul_f32 v[96:97], v[96:97], v[0:1] op_sel_hi:[1,0]
	v_pk_fma_f32 v[94:95], v[6:7], v[94:95], v[10:11]
	v_pk_fma_f32 v[96:97], v[8:9], v[96:97], v[12:13]
	v_bfe_u32 v156, v94, 16, 1
	v_add3_u32 v94, v94, v156, s94
	v_bfe_u32 v156, v95, 16, 1
	v_lshrrev_b32_e32 v94, 16, v94
	v_add3_u32 v95, v95, v156, s94
	v_and_or_b32 v94, v95, s95, v94
	v_bfe_u32 v95, v96, 16, 1
	v_add3_u32 v95, v96, v95, s94
	v_bfe_u32 v96, v97, 16, 1
	v_lshrrev_b32_e32 v95, 16, v95
	v_add3_u32 v96, v97, v96, s94
	v_pk_mul_f32 v[82:83], v[82:83], v[0:1] op_sel_hi:[1,0]
	v_lshrrev_b32_e32 v155, 4, v130
	v_lshlrev_b32_e32 v155, 15, v155
	v_and_b32_e32 v200, 15, v130
	v_lshl_or_b32 v155, v200, 3, v155
	v_and_or_b32 v95, v96, s95, v95
	v_pk_fma_f32 v[82:83], v[26:27], v[82:83], v[22:23]
	global_store_dwordx2 v155, v[94:95], s[6:7]
	v_bfe_u32 v94, v82, 16, 1
	v_pk_mul_f32 v[84:85], v[84:85], v[0:1] op_sel_hi:[1,0]
	v_add3_u32 v82, v82, v94, s94
	v_bfe_u32 v94, v83, 16, 1
	v_pk_fma_f32 v[84:85], v[28:29], v[84:85], v[24:25]
	v_lshrrev_b32_e32 v82, 16, v82
	v_add3_u32 v83, v83, v94, s94
	v_and_or_b32 v82, v83, s95, v82
	v_bfe_u32 v83, v84, 16, 1
	v_add3_u32 v83, v84, v83, s94
	v_bfe_u32 v84, v85, 16, 1
	v_lshrrev_b32_e32 v83, 16, v83
	v_add3_u32 v84, v85, v84, s94
	v_pk_mul_f32 v[46:47], v[46:47], v[0:1] op_sel_hi:[1,0]
	v_and_or_b32 v83, v84, s95, v83
	v_pk_fma_f32 v[46:47], v[42:43], v[46:47], v[38:39]
	s_add_u32 s6, s6, 0x20000
	s_addc_u32 s7, s7, 0
	global_store_dwordx2 v155, v[82:83], s[6:7]
	v_bfe_u32 v82, v46, 16, 1
	v_pk_mul_f32 v[48:49], v[48:49], v[0:1] op_sel_hi:[1,0]
	v_add3_u32 v46, v46, v82, s94
	v_bfe_u32 v82, v47, 16, 1
	v_pk_fma_f32 v[48:49], v[44:45], v[48:49], v[40:41]
	v_lshrrev_b32_e32 v46, 16, v46
	v_add3_u32 v47, v47, v82, s94
	v_and_or_b32 v46, v47, s95, v46
	v_bfe_u32 v47, v48, 16, 1
	v_add3_u32 v47, v48, v47, s94
	v_bfe_u32 v48, v49, 16, 1
	v_lshrrev_b32_e32 v47, 16, v47
	v_add3_u32 v48, v49, v48, s94
	v_pk_mul_f32 v[34:35], v[34:35], v[0:1] op_sel_hi:[1,0]
	v_and_or_b32 v47, v48, s95, v47
	v_pk_fma_f32 v[34:35], v[90:91], v[34:35], v[78:79]
	s_add_u32 s6, s6, 0x20000
	s_addc_u32 s7, s7, 0
	global_store_dwordx2 v155, v[46:47], s[6:7]
	v_bfe_u32 v46, v34, 16, 1
	v_pk_mul_f32 v[36:37], v[36:37], v[0:1] op_sel_hi:[1,0]
	v_add3_u32 v34, v34, v46, s94
	v_bfe_u32 v46, v35, 16, 1
	v_pk_fma_f32 v[36:37], v[92:93], v[36:37], v[80:81]
	v_lshrrev_b32_e32 v34, 16, v34
	v_add3_u32 v35, v35, v46, s94
	v_and_or_b32 v34, v35, s95, v34
	v_bfe_u32 v35, v36, 16, 1
	v_add3_u32 v35, v36, v35, s94
	v_bfe_u32 v36, v37, 16, 1
	v_lshrrev_b32_e32 v35, 16, v35
	v_add3_u32 v36, v37, v36, s94
	v_pk_mul_f32 v[30:31], v[30:31], v[0:1] op_sel_hi:[1,0]
	v_and_or_b32 v35, v36, s95, v35
	v_pk_fma_f32 v[30:31], v[102:103], v[30:31], v[98:99]
	s_add_u32 s6, s6, 0x20000
	s_addc_u32 s7, s7, 0
	global_store_dwordx2 v155, v[34:35], s[6:7]
	v_bfe_u32 v34, v30, 16, 1
	v_pk_mul_f32 v[32:33], v[32:33], v[0:1] op_sel_hi:[1,0]
	v_add3_u32 v30, v30, v34, s94
	v_bfe_u32 v34, v31, 16, 1
	v_pk_fma_f32 v[32:33], v[104:105], v[32:33], v[100:101]
	v_lshrrev_b32_e32 v30, 16, v30
	v_add3_u32 v31, v31, v34, s94
	v_and_or_b32 v30, v31, s95, v30
	v_bfe_u32 v31, v32, 16, 1
	v_add3_u32 v31, v32, v31, s94
	v_bfe_u32 v32, v33, 16, 1
	v_lshrrev_b32_e32 v31, 16, v31
	v_add3_u32 v32, v33, v32, s94
	v_pk_mul_f32 v[18:19], v[18:19], v[0:1] op_sel_hi:[1,0]
	v_and_or_b32 v31, v32, s95, v31
	v_pk_fma_f32 v[18:19], v[110:111], v[18:19], v[106:107]
	s_add_u32 s6, s6, 0x20000
	s_addc_u32 s7, s7, 0
	global_store_dwordx2 v155, v[30:31], s[6:7]
	v_bfe_u32 v30, v18, 16, 1
	v_pk_mul_f32 v[20:21], v[20:21], v[0:1] op_sel_hi:[1,0]
	v_add3_u32 v18, v18, v30, s94
	v_bfe_u32 v30, v19, 16, 1
	v_pk_fma_f32 v[20:21], v[112:113], v[20:21], v[108:109]
	v_lshrrev_b32_e32 v18, 16, v18
	v_add3_u32 v19, v19, v30, s94
	v_and_or_b32 v18, v19, s95, v18
	v_bfe_u32 v19, v20, 16, 1
	v_add3_u32 v19, v20, v19, s94
	v_bfe_u32 v20, v21, 16, 1
	v_lshrrev_b32_e32 v19, 16, v19
	v_add3_u32 v20, v21, v20, s94
	v_pk_mul_f32 v[14:15], v[14:15], v[0:1] op_sel_hi:[1,0]
	v_pk_mul_f32 v[2:3], v[2:3], v[0:1] op_sel_hi:[1,0]
	v_and_or_b32 v19, v20, s95, v19
	v_pk_fma_f32 v[14:15], v[118:119], v[14:15], v[114:115]
	s_waitcnt vmcnt(5)
; __device__ __forceinline__ unsigned pk2(float lo, float hi) { return f2bf(lo) | (f2bf(hi) << 16); }
; __device__ __forceinline__ void modulate_phase(Frame& F, const float* x, bf16* H, const float* gnorm, const float* modsub) {
;     ...
;         for (int j = 0; j < 8; ++j) { const f32x4 y = v[j] * rstd * gs[j] + sh[j];
;             o8[64 * j] = (unsigned long long)pk2(y.x, y.y) | ((unsigned long long)pk2(y.z, y.w) << 32); }
; #pragma unroll
;         for (int j = 0; j < 8; ++j) v[j] = nv[j];
;     }
	v_pk_fma_f32 v[2:3], v[122:123], v[2:3], v[126:127]
	s_add_u32 s6, s6, 0x20000
	s_addc_u32 s7, s7, 0
	global_store_dwordx2 v155, v[18:19], s[6:7]
	v_pk_mul_f32 v[16:17], v[16:17], v[0:1] op_sel_hi:[1,0]
	v_bfe_u32 v18, v14, 16, 1
	v_pk_mul_f32 v[4:5], v[4:5], v[0:1] op_sel_hi:[1,0]
	v_bfe_u32 v0, v2, 16, 1
	v_add3_u32 v14, v14, v18, s94
	v_bfe_u32 v18, v15, 16, 1
	v_add3_u32 v0, v2, v0, s94
	v_bfe_u32 v2, v3, 16, 1
	v_pk_fma_f32 v[16:17], v[120:121], v[16:17], v[116:117]
	v_lshrrev_b32_e32 v14, 16, v14
	v_add3_u32 v15, v15, v18, s94
	v_pk_fma_f32 v[4:5], v[124:125], v[4:5], v[128:129]
	v_lshrrev_b32_e32 v0, 16, v0
	v_add3_u32 v2, v3, v2, s94
	v_and_or_b32 v14, v15, s95, v14
	v_bfe_u32 v15, v16, 16, 1
	v_and_or_b32 v2, v2, s95, v0
	v_bfe_u32 v0, v4, 16, 1
	v_add3_u32 v15, v16, v15, s94
	v_bfe_u32 v16, v17, 16, 1
	v_add3_u32 v0, v4, v0, s94
	v_bfe_u32 v3, v5, 16, 1
	v_lshrrev_b32_e32 v15, 16, v15
	v_add3_u32 v16, v17, v16, s94
	v_lshrrev_b32_e32 v0, 16, v0
	v_add3_u32 v3, v5, v3, s94
	v_and_or_b32 v15, v16, s95, v15
	v_and_or_b32 v3, v3, s95, v0
	s_add_u32 s6, s6, 0x20000
	s_addc_u32 s7, s7, 0
	global_store_dwordx2 v155, v[14:15], s[6:7]
	s_add_u32 s6, s6, 0x20000
	s_addc_u32 s7, s7, 0
	global_store_dwordx2 v155, v[2:3], s[6:7]
	s_sub_u32 s6, s6, 0xdff80
	s_subb_u32 s7, s7, 0
	s_cmp_lt_i32 s0, s2
	v_mov_b32_e32 v94, v86
	v_mov_b32_e32 v95, v87
	v_mov_b32_e32 v96, v88
	v_mov_b32_e32 v97, v89
	v_mov_b32_e32 v82, v74
	v_mov_b32_e32 v83, v75
	v_mov_b32_e32 v84, v76
	v_mov_b32_e32 v85, v77
	v_mov_b32_e32 v46, v66
	v_mov_b32_e32 v47, v67
	v_mov_b32_e32 v48, v68
	v_mov_b32_e32 v49, v69
	v_mov_b32_e32 v34, v58
	v_mov_b32_e32 v35, v59
	v_mov_b32_e32 v36, v60
	v_mov_b32_e32 v37, v61
	v_mov_b32_e32 v30, v70
	v_mov_b32_e32 v31, v71
	v_mov_b32_e32 v32, v72
	v_mov_b32_e32 v33, v73
	v_mov_b32_e32 v18, v62
	v_mov_b32_e32 v19, v63
	v_mov_b32_e32 v20, v64
	v_mov_b32_e32 v21, v65
	v_mov_b32_e32 v14, v54
	v_mov_b32_e32 v15, v55
	v_mov_b32_e32 v16, v56
	v_mov_b32_e32 v17, v57
	v_mov_b32_e32 v2, v50
	v_mov_b32_e32 v3, v51
	v_mov_b32_e32 v4, v52
	v_mov_b32_e32 v5, v53
	s_cbranch_scc0 .LBB0_1737

; template <class Epi, class Sched, bool ALIGN_EPI = false, bool SP2 = false>
; __device__ __forceinline__ void gemm_phase(PG8_LAS unsigned char* lds, const Gemm g, const Sched& S, const Epi& E, int wave_s) {
;     int tid_ = (wave_s << 6) | fresh_lane(); asm volatile("" : "+v"(tid_));
;     const int tid = tid_, wid = __builtin_amdgcn_readfirstlane(tid >> 6), lane = tid & 63, wr = wid >> 2, wc = wid & 3, fr = lane & 15, fq = lane >> 4;
;     const int K = g.K, nt = K / BK;
;     unsigned voffA[2], voffB[2];
; #pragma unroll
;     for (int i = 0; i < 2; ++i) { int R, C; stage_rc(tid * 16 + i * 8192, R, C); const int Rb = Epi::PERM ? ((R & ~31) + perm32(R & 31)) : R;
;         voffA[i] = (unsigned)(R * g.lda + C) * 2u; voffB[i] = (unsigned)(Rb * g.ldb + C) * 2u; }
;     const size_t kstep = (size_t)(BK * 2);
;     const size_t hstepA = (size_t)HALF * g.lda * 2, hstepB = (size_t)HALF * g.ldb * 2;
;     const size_t tstepA = 2 * hstepA, tstepB = 2 * hstepB;
;     const unsigned ldsw = (unsigned)wid * 1024u;
;     const int aoff = lds_byte(wr * 64 + fr, fq * 8), boff = lds_byte(wc * 32 + fr, fq * 8);
;     ...
;     Unit cur, nxt; int ui = 0;
;     if (!S.next(0, cur)) return;
;     f32x4 acc[2][2][4][2];
; #pragma unroll
;     for (int a = 0; a < 2; ++a)
; #pragma unroll
;         for (int b = 0; b < 2; ++b)
; #pragma unroll
;             for (int m = 0; m < 4; ++m)
; #pragma unroll
;                 for (int n = 0; n < 2; ++n) acc[a][b][m][n] = (f32x4){0.f, 0.f, 0.f, 0.f};
;     bf16x8 At[4][2], B0[2][2], B1[2][2];
;     const char* cA = (const char*)g.A + (size_t)cur.pm * tstepA; const char* cB = (const char*)g.Bt + (size_t)cur.pn * tstepB;
;     S.a_ready(cur);
;     if constexpr (SP2) {
;         PG8_STAGE(PG8_SB(0, 0), cB, voffB); PG8_STAGE(PG8_SB(0, 1), cB + hstepB, voffB); PG8_STAGE(PG8_SA(0, 0), cA, voffA); PG8_STAGE(PG8_SA(0, 1), cA + hstepA, voffA);
;         if (wr == 1) PG8_BAR;
;         PG8_WAIT_V(2); PG8_BAR;
;         PG8_STAGE(PG8_SB(1, 0), cB + kstep, voffB); PG8_STAGE(PG8_SA(1, 0), cA + kstep, voffA); PG8_STAGE(PG8_SB(1, 1), cB + hstepB + kstep, voffB);
;         PG8_WAIT_V(6); PG8_BAR;
;     } else {
;         PG8_STAGE(PG8_SB(0, 0), cB, voffB); PG8_STAGE(PG8_SA(0, 0), cA, voffA); PG8_STAGE(PG8_SB(0, 1), cB + hstepB, voffB); PG8_STAGE(PG8_SA(0, 1), cA + hstepA, voffA);
;         if (wr == 1) PG8_BAR;
;         PG8_WAIT_V(4); PG8_BAR;
.LBB0_1787:
	s_andn2_b64 vcc, exec, s[0:1]
	s_cbranch_vccnz .LBB0_1852
	s_load_dwordx2 s[6:7], s[82:83], 0xb8
	v_mov_b32_e32 v0, v1
	s_waitcnt lgkmcnt(0)
	v_readlane_b32 s0, v253, 21
	v_mbcnt_lo_u32_b32 v0, -1, v0
	v_mbcnt_hi_u32_b32 v0, -1, v0
	v_or_b32_e32 v0, s0, v0
	s_nop 0
	v_readfirstlane_b32 s0, v0
	v_mov_b32_e32 v0, v1
	s_andn2_b32 s0, s0, 63
	v_mbcnt_lo_u32_b32 v0, -1, v0
	v_mbcnt_hi_u32_b32 v0, -1, v0
	v_or_b32_e32 v16, s0, v0
	v_readlane_b32 s0, v255, 49
	v_readlane_b32 s1, v255, 50
	s_and_b64 vcc, exec, s[0:1]
	v_readfirstlane_b32 s8, v16
	s_cbranch_vccnz .LBB0_1804
	v_lshlrev_b32_e32 v0, 4, v16
	v_add_u32_e32 v2, 0x2000, v0
	v_ashrrev_i32_e32 v3, 31, v2
	v_lshrrev_b32_e32 v3, 22, v3
	v_add_u32_e32 v3, v2, v3
	v_ashrrev_i32_e32 v10, 10, v3
	v_mul_i32_i24_e32 v3, 0x400, v10
	v_sub_u32_e32 v2, v2, v3
	v_lshrrev_b32_e32 v3, 4, v2
	v_bitop3_b32 v2, v3, v2, 32 bitop3:0x6c
	v_ashrrev_i32_e32 v3, 31, v2
	s_add_u32 s2, s6, 0x1ed90000
	v_lshrrev_b32_e32 v3, 26, v3
	s_addc_u32 s22, s7, 0
	s_mul_i32 s0, s78, 0x5800000
	v_add_u32_e32 v3, v2, v3
	v_lshlrev_b32_e32 v4, 3, v10
	s_add_u32 s0, s6, s0
	v_ashrrev_i32_e32 v11, 6, v3
	v_and_b32_e32 v4, -16, v4
	s_addc_u32 s1, s7, 0
	v_add_u32_e32 v4, v11, v4
	s_add_u32 s40, s0, 0x2d90000
	v_and_b32_e32 v5, 3, v11
	s_mov_b32 s0, 0xfffe0
	v_lshrrev_b32_e32 v6, 2, v4
	v_lshlrev_b32_e32 v7, 1, v4
	v_and_or_b32 v5, v4, s0, v5
	v_and_b32_e32 v6, 4, v6
	v_and_b32_e32 v7, 24, v7
	v_and_b32_e32 v3, 0xc0, v3
	v_or3_b32 v5, v5, v6, v7
	v_sub_u32_e32 v2, v2, v3
	v_mov_b32_e32 v7, 1
	v_lshlrev_b32_e32 v6, 5, v10
	v_ashrrev_i16_sdwa v2, v7, sext(v2) dst_sel:DWORD dst_unused:UNUSED_PAD src0_sel:DWORD src1_sel:BYTE_0
	v_and_b32_e32 v6, 32, v6
	v_bfe_i32 v12, v2, 0, 16
	v_add_lshl_u32 v2, v6, v12, 1
	s_waitcnt vmcnt(0)
	v_lshl_add_u32 v130, v5, 7, v2
	v_lshl_add_u32 v132, v4, 7, v2
	v_bfe_i32 v2, v16, 27, 1
	v_lshrrev_b32_e32 v2, 22, v2
	v_add_u32_e32 v2, v0, v2
	v_and_b32_e32 v2, 0xfffffc00, v2
	v_sub_u32_e32 v0, v0, v2
	v_lshrrev_b32_e32 v2, 4, v0
	v_ashrrev_i32_e32 v3, 31, v16
	v_bitop3_b32 v0, v2, v0, 32 bitop3:0x6c
	v_lshrrev_b32_e32 v3, 26, v3
	v_ashrrev_i32_e32 v2, 31, v0
	v_add_u32_e32 v3, v16, v3
	v_lshrrev_b32_e32 v2, 26, v2
	v_ashrrev_i32_e32 v14, 6, v3
	v_add_u32_e32 v2, v0, v2
	v_lshlrev_b32_e32 v3, 3, v14
	v_ashrrev_i32_e32 v13, 6, v2
	v_and_b32_e32 v3, -16, v3
	v_add_u32_e32 v3, v13, v3
	v_and_b32_e32 v4, 3, v13
	v_lshrrev_b32_e32 v5, 2, v3
	v_lshlrev_b32_e32 v6, 1, v3
	v_and_b32_e32 v2, 0xc0, v2
	s_addc_u32 s41, s1, 0
	s_ashr_i32 s9, s8, 6
	v_and_or_b32 v4, v3, s0, v4
	v_and_b32_e32 v5, 4, v5
	v_and_b32_e32 v6, 24, v6
	v_sub_u32_e32 v0, v0, v2
	s_ashr_i32 s10, s8, 8
	s_lshl_b32 s42, s9, 10
	v_or3_b32 v4, v4, v5, v6
	v_lshlrev_b32_e32 v5, 5, v14
	v_ashrrev_i16_sdwa v0, v7, sext(v0) dst_sel:DWORD dst_unused:UNUSED_PAD src0_sel:DWORD src1_sel:BYTE_0
	v_readlane_b32 s0, v254, 47
	v_and_b32_e32 v5, 32, v5
	v_bfe_i32 v15, v0, 0, 16
	v_readlane_b32 s1, v254, 48
	s_add_u32 s18, s40, s0
	v_add_lshl_u32 v2, v5, v15, 1
	s_addc_u32 s19, s41, s1
	s_add_i32 s43, s42, 0
	v_lshl_add_u32 v0, v4, 7, v2
	s_add_i32 m0, s43, 0x10000
	v_lshl_add_u32 v134, v3, 7, v2
	global_load_lds_dwordx4 v0, s[18:19]
	s_add_i32 m0, s43, 0x12000
	s_add_u32 s0, s18, 0x4000
	global_load_lds_dwordx4 v130, s[18:19]
	s_addc_u32 s1, s19, 0
	s_add_i32 m0, s43, 0x14000
	v_mov_b32_e32 v131, v1
	global_load_lds_dwordx4 v0, s[0:1]
	s_add_i32 m0, s43, 0x16000
	v_mov_b32_e32 v135, v1
	global_load_lds_dwordx4 v130, s[0:1]
	v_readlane_b32 s0, v254, 56
	v_readlane_b32 s1, v254, 57
	s_add_u32 s20, s2, s0
	s_addc_u32 s21, s22, s1
	s_add_i32 s44, s43, 0x2000
	s_mov_b32 m0, s43
	s_add_u32 s0, s20, 0x4000
	global_load_lds_dwordx4 v134, s[20:21]
	s_mov_b32 m0, s44
	s_addc_u32 s1, s21, 0
	s_add_i32 s45, s43, 0x4000
	global_load_lds_dwordx4 v132, s[20:21]
	s_mov_b32 m0, s45
	s_add_i32 s46, s43, 0x6000
	global_load_lds_dwordx4 v134, s[0:1]
	s_mov_b32 m0, s46
	v_mov_b32_e32 v133, v1
	global_load_lds_dwordx4 v132, s[0:1]
	s_cmp_eq_u32 s10, 1
	v_lshl_add_u64 v[8:9], s[18:19], 0, v[0:1]
	v_lshl_add_u64 v[6:7], s[18:19], 0, v[130:131]
	v_lshl_add_u64 v[2:3], s[20:21], 0, v[134:135]
	s_cselect_b64 s[0:1], -1, 0
	s_cmp_lg_u32 s10, 1
	v_lshl_add_u64 v[4:5], s[20:21], 0, v[132:133]
	s_cbranch_scc1 .LBB0_1791
	s_barrier
.LBB0_1791:
	s_add_u32 s6, s6, 0x22d90000
	v_lshrrev_b32_e32 v18, 1, v16
	s_addc_u32 s7, s7, 0
	v_and_b32_e32 v18, 24, v18
	s_lshl_b32 s9, s9, 5
	v_and_b32_e32 v17, 15, v16
	v_lshlrev_b32_e32 v19, 1, v18
	v_lshlrev_b32_e32 v16, 2, v16
	s_and_b32 s12, s9, 0x60
	s_add_i32 m0, s43, 0x18000
	s_mov_b64 s[100:101], 0x8000
	v_lshl_add_u64 v[8:9], v[8:9], 0, s[100:101]
	v_lshl_or_b32 v142, s10, 6, v17
	v_lshl_or_b32 v17, v17, 6, v19
	s_lshl_b32 s10, s10, 13
	v_and_b32_e32 v16, 32, v16
	s_lshl_b32 s9, s12, 7
	s_waitcnt vmcnt(2)
	s_barrier
	global_load_lds_dwordx4 v[8:9], off
	v_lshl_add_u64 v[6:7], v[6:7], 0, s[100:101]
	s_add_i32 m0, s43, 0x1a000
	s_add_i32 s47, s43, 0x8000
	s_add_i32 s48, s43, 0xa000
	v_bitop3_b32 v19, v17, s10, v16 bitop3:0xde
	global_load_lds_dwordx4 v[6:7], off
	s_mov_b64 s[100:101], 0x8000
	v_lshl_add_u64 v[2:3], v[2:3], 0, s[100:101]
	s_mov_b32 m0, s47
	s_add_u32 s10, s18, 0xc000
	global_load_lds_dwordx4 v[2:3], off
	v_lshl_add_u64 v[2:3], v[4:5], 0, s[100:101]
	s_mov_b32 m0, s48
	s_addc_u32 s11, s19, 0
	global_load_lds_dwordx4 v[2:3], off
	s_add_i32 m0, s43, 0x1c000
	v_lshl_add_u64 v[2:3], s[10:11], 0, v[0:1]
	global_load_lds_dwordx4 v[2:3], off
	v_lshl_add_u64 v[2:3], s[10:11], 0, v[130:131]
	s_add_i32 m0, s43, 0x1e000
	s_cmpk_lt_u32 s8, 0x100
	global_load_lds_dwordx4 v[2:3], off
	v_lshlrev_b32_e32 v2, 10, v10
	v_and_b32_e32 v2, 0xfffff800, v2
	v_lshl_add_u32 v2, v11, 7, v2
	v_and_b32_e32 v3, 1, v10
	v_lshl_or_b32 v2, v3, 6, v2
	v_lshl_add_u32 v136, v12, 1, v2
	v_lshlrev_b32_e32 v2, 10, v14
	v_and_b32_e32 v2, 0xfffff800, v2
	s_waitcnt vmcnt(6)
	v_lshl_add_u32 v2, v13, 7, v2
	v_and_b32_e32 v3, 1, v14
	v_lshl_or_b32 v2, v3, 6, v2
	v_readlane_b32 s10, v254, 54
	v_bitop3_b32 v143, v17, s9, v16 bitop3:0xde
	s_cselect_b64 s[8:9], -1, 0
	v_or_b32_e32 v144, s12, v18
	v_mov_b32_e32 v137, v1
	v_lshl_add_u32 v138, v15, 1, v2
	v_mov_b32_e32 v139, v1
	s_mov_b32 s49, 0
	v_add_u32_e32 v145, 0, v19
	v_readlane_b32 s26, v254, 46
	s_mov_b32 s27, s10
	s_barrier
	v_readlane_b32 s11, v254, 55
	s_branch .LBB0_1794

; #define PG8_STAGE(bufoff, gbase, voff) do { _Pragma("unroll") for (int _i = 0; _i < 2; ++_i) \
;         __builtin_amdgcn_global_load_lds((const unsigned*)((const char*)(gbase) + (voff)[_i]), (PG8_LAS unsigned*)(lds + (bufoff) + ldsw + _i * 8192), 16, 0, 0); } while (0)
; #define PG8_LDA(dst, b, h) do { _Pragma("unroll") for (int m = 0; m < 4; ++m) _Pragma("unroll") for (int k = 0; k < 2; ++k) dst[m][k] = *(const PG8_LAS bf16x8*)(lds + PG8_SA(b, h) + aoff + m * 2048 + k * 1024); } while (0)
; #define PG8_LDB(dst, b, h) do { _Pragma("unroll") for (int n = 0; n < 2; ++n) _Pragma("unroll") for (int k = 0; k < 2; ++k) dst[n][k] = *(const PG8_LAS bf16x8*)(lds + PG8_SB(b, h) + boff + n * 2048 + k * 1024); } while (0)
; #define PG8_MMA(ai, bj, At, Bt) do { __builtin_amdgcn_s_setprio(1); _Pragma("unroll") for (int m = 0; m < 4; ++m) _Pragma("unroll") for (int n = 0; n < 2; ++n) _Pragma("unroll") for (int k = 0; k < 2; ++k) \
;         acc[ai][bj][m][n] = __builtin_amdgcn_mfma_f32_16x16x32_bf16(Bt[n][k], At[m][k], acc[ai][bj][m][n], 0, 0, 0); __builtin_amdgcn_s_setprio(0); } while (0)
; #define PG8_WAIT_V(n) asm volatile("s_waitcnt vmcnt(" #n ")" ::: "memory")
; template <class Epi, class Sched, bool ALIGN_EPI = false, bool SP2 = false>
; __device__ __forceinline__ void gemm_phase(PG8_LAS unsigned char* lds, const Gemm g, const Sched& S, const Epi& E, int wave_s) {
;     ...
;         const bool has_next = S.next(ui + 1, nxt);
;         const char* nA = has_next ? (const char*)g.A + (size_t)nxt.pm * tstepA : cA; const char* nB = has_next ? (const char*)g.Bt + (size_t)nxt.pn * tstepB : cB;
;         for (int t = 0; t < nt; t += 2) {
;             const bool last = (t == nt - 2);
;             const char* a1 = cA + (size_t)(t + 1) * kstep;
;             const char* a2 = last ? nA : cA + (size_t)(t + 2) * kstep; const char* b2 = last ? nB : cB + (size_t)(t + 2) * kstep;
;             const char* a3 = a2 + kstep; const char* b3 = b2 + kstep;
;             if (last && has_next) S.a_ready(nxt);
;             if constexpr (Epi::HAS_MID) { if (t == nt / 2) E.mid(acc, cur, wr, wc, fr, fq); }
;             if constexpr (SP2) {
;             PG8_LDB(B0, 0, 0); PG8_LDB(B1, 0, 1); PG8_SCHED; PG8_LDA(At, 0, 0); PG8_STAGE(PG8_SA(1, 1), a1 + hstepA, voffA);
;             PG8_WAIT_V(8); PG8_WAIT_L(0); PG8_BAR; PG8_MMA(0, 0, At, B0); PG8_MMA(0, 1, At, B1); PG8_BAR; PG8_SCHED;
.LBB0_1796:
	s_ashr_i32 s13, s12, 31
	s_lshl_b64 s[14:15], s[12:13], 20
	s_add_u32 s14, s2, s14
	s_addc_u32 s15, s22, s15
	s_and_b64 s[16:17], s[36:37], exec
	s_cselect_b32 s13, s15, s21
	s_cselect_b32 s33, s14, s20
	s_ashr_i32 s11, s10, 31
	s_lshl_b64 s[16:17], s[10:11], 20
	s_add_u32 s16, s40, s16
	s_addc_u32 s17, s41, s17
	s_and_b64 s[24:25], s[36:37], exec
	s_cselect_b32 s11, s17, s19
	s_cselect_b32 s50, s16, s18
	s_add_u32 s51, s18, 0x10000
	s_addc_u32 s54, s19, 0
	s_add_u32 s18, s20, 0xc000
	v_mov_b32_e32 v2, 0
	s_addc_u32 s19, s21, 0
	s_mov_b32 s55, -2
	v_mov_b32_e32 v3, v2
	v_mov_b32_e32 v4, v2
	v_mov_b32_e32 v5, v2
	v_mov_b32_e32 v10, v2
	v_mov_b32_e32 v11, v2
	v_mov_b32_e32 v12, v2
	v_mov_b32_e32 v13, v2
	v_mov_b32_e32 v18, v2
	v_mov_b32_e32 v19, v2
	v_mov_b32_e32 v20, v2
	v_mov_b32_e32 v21, v2
	v_mov_b32_e32 v26, v2
	v_mov_b32_e32 v27, v2
	v_mov_b32_e32 v28, v2
	v_mov_b32_e32 v29, v2
	v_mov_b32_e32 v34, v2
	v_mov_b32_e32 v35, v2
	v_mov_b32_e32 v36, v2
	v_mov_b32_e32 v37, v2
	v_mov_b32_e32 v42, v2
	v_mov_b32_e32 v43, v2
	v_mov_b32_e32 v44, v2
	v_mov_b32_e32 v45, v2
	v_mov_b32_e32 v50, v2
	v_mov_b32_e32 v51, v2
	v_mov_b32_e32 v52, v2
	v_mov_b32_e32 v53, v2
	v_mov_b32_e32 v58, v2
	v_mov_b32_e32 v59, v2
	v_mov_b32_e32 v60, v2
	v_mov_b32_e32 v61, v2
	v_mov_b32_e32 v6, v2
	v_mov_b32_e32 v7, v2
	v_mov_b32_e32 v8, v2
	v_mov_b32_e32 v9, v2
	v_mov_b32_e32 v14, v2
	v_mov_b32_e32 v15, v2
	v_mov_b32_e32 v16, v2
	v_mov_b32_e32 v17, v2
	v_mov_b32_e32 v22, v2
	v_mov_b32_e32 v23, v2
	v_mov_b32_e32 v24, v2
	v_mov_b32_e32 v25, v2
	v_mov_b32_e32 v30, v2
	v_mov_b32_e32 v31, v2
	v_mov_b32_e32 v32, v2
	v_mov_b32_e32 v33, v2
	v_mov_b32_e32 v38, v2
	v_mov_b32_e32 v39, v2
	v_mov_b32_e32 v40, v2
	v_mov_b32_e32 v41, v2
	v_mov_b32_e32 v46, v2
	v_mov_b32_e32 v47, v2
	v_mov_b32_e32 v48, v2
	v_mov_b32_e32 v49, v2
	v_mov_b32_e32 v54, v2
	v_mov_b32_e32 v55, v2
	v_mov_b32_e32 v56, v2
	v_mov_b32_e32 v57, v2
	v_mov_b32_e32 v62, v2
	v_mov_b32_e32 v63, v2
	v_mov_b32_e32 v64, v2
	v_mov_b32_e32 v65, v2
	v_mov_b32_e32 v66, v2
	v_mov_b32_e32 v67, v2
	v_mov_b32_e32 v68, v2
	v_mov_b32_e32 v69, v2
	v_mov_b32_e32 v74, v2
	v_mov_b32_e32 v75, v2
	v_mov_b32_e32 v76, v2
	v_mov_b32_e32 v77, v2
	v_mov_b32_e32 v82, v2
	v_mov_b32_e32 v83, v2
	v_mov_b32_e32 v84, v2
	v_mov_b32_e32 v85, v2
	v_mov_b32_e32 v90, v2
	v_mov_b32_e32 v91, v2
	v_mov_b32_e32 v92, v2
	v_mov_b32_e32 v93, v2
	v_mov_b32_e32 v98, v2
	v_mov_b32_e32 v99, v2
	v_mov_b32_e32 v100, v2
	v_mov_b32_e32 v101, v2
	v_mov_b32_e32 v106, v2
	v_mov_b32_e32 v107, v2
	v_mov_b32_e32 v108, v2
	v_mov_b32_e32 v109, v2
	v_mov_b32_e32 v114, v2
	v_mov_b32_e32 v115, v2
	v_mov_b32_e32 v116, v2
	v_mov_b32_e32 v117, v2
	v_mov_b32_e32 v122, v2
	v_mov_b32_e32 v123, v2
	v_mov_b32_e32 v124, v2
	v_mov_b32_e32 v125, v2
	v_mov_b32_e32 v70, v2
	v_mov_b32_e32 v71, v2
	v_mov_b32_e32 v72, v2
	v_mov_b32_e32 v73, v2
	v_mov_b32_e32 v78, v2
	v_mov_b32_e32 v79, v2
	v_mov_b32_e32 v80, v2
	v_mov_b32_e32 v81, v2
	v_mov_b32_e32 v86, v2
	v_mov_b32_e32 v87, v2
	v_mov_b32_e32 v88, v2
	v_mov_b32_e32 v89, v2
	v_mov_b32_e32 v94, v2
	v_mov_b32_e32 v95, v2
	v_mov_b32_e32 v96, v2
	v_mov_b32_e32 v97, v2
	v_mov_b32_e32 v102, v2
	v_mov_b32_e32 v103, v2
	v_mov_b32_e32 v104, v2
	v_mov_b32_e32 v105, v2
	v_mov_b32_e32 v110, v2
	v_mov_b32_e32 v111, v2
	v_mov_b32_e32 v112, v2
	v_mov_b32_e32 v113, v2
	v_mov_b32_e32 v118, v2
	v_mov_b32_e32 v119, v2
	v_mov_b32_e32 v120, v2
	v_mov_b32_e32 v121, v2
	v_mov_b32_e32 v126, v2
	v_mov_b32_e32 v127, v2
	v_mov_b32_e32 v128, v2
	v_mov_b32_e32 v129, v2
.LBB0_1797:
	s_add_u32 s20, s18, 0x4000
	s_addc_u32 s21, s19, 0
	s_add_i32 s34, 0, 0x10000
	s_cmp_eq_u32 s55, 28
	s_cselect_b32 s25, s13, s21
	s_cselect_b32 s24, s33, s20
	v_add_u32_e32 v140, s34, v143
	s_cselect_b32 s21, s11, s54
	s_cselect_b32 s20, s50, s51
	s_add_i32 s56, 0, 0x14000
	ds_read_b128 v[146:149], v140
	ds_read_b128 v[150:153], v140 offset:1024
	ds_read_b128 v[154:157], v140 offset:2048
	ds_read_b128 v[158:161], v140 offset:3072
	v_add_u32_e32 v140, s56, v143
	ds_read_b128 v[162:165], v140
	ds_read_b128 v[166:169], v140 offset:1024
	ds_read_b128 v[176:179], v140 offset:2048
	ds_read_b128 v[180:183], v140 offset:3072
	v_lshl_add_u64 v[140:141], s[18:19], 0, v[138:139]
	s_add_i32 m0, s43, 0xc000
	ds_read_b128 v[184:187], v145
	ds_read_b128 v[188:191], v145 offset:1024
	ds_read_b128 v[192:195], v145 offset:2048
	ds_read_b128 v[196:199], v145 offset:3072
	ds_read_b128 v[208:211], v145 offset:4096
	ds_read_b128 v[212:215], v145 offset:5120
	ds_read_b128 v[216:219], v145 offset:6144
	ds_read_b128 v[220:223], v145 offset:7168
	global_load_lds_dwordx4 v[140:141], off
	v_lshl_add_u64 v[140:141], s[18:19], 0, v[136:137]
	s_add_i32 m0, s43, 0xe000
	s_nop 0
	global_load_lds_dwordx4 v[140:141], off
	s_waitcnt vmcnt(8)
	s_waitcnt lgkmcnt(0)
	s_barrier
; #define PG8_STAGE(bufoff, gbase, voff) do { _Pragma("unroll") for (int _i = 0; _i < 2; ++_i) \
;         __builtin_amdgcn_global_load_lds((const unsigned*)((const char*)(gbase) + (voff)[_i]), (PG8_LAS unsigned*)(lds + (bufoff) + ldsw + _i * 8192), 16, 0, 0); } while (0)
; #define PG8_LDA(dst, b, h) do { _Pragma("unroll") for (int m = 0; m < 4; ++m) _Pragma("unroll") for (int k = 0; k < 2; ++k) dst[m][k] = *(const PG8_LAS bf16x8*)(lds + PG8_SA(b, h) + aoff + m * 2048 + k * 1024); } while (0)
; #define PG8_MMA(ai, bj, At, Bt) do { __builtin_amdgcn_s_setprio(1); _Pragma("unroll") for (int m = 0; m < 4; ++m) _Pragma("unroll") for (int n = 0; n < 2; ++n) _Pragma("unroll") for (int k = 0; k < 2; ++k) \
;         acc[ai][bj][m][n] = __builtin_amdgcn_mfma_f32_16x16x32_bf16(Bt[n][k], At[m][k], acc[ai][bj][m][n], 0, 0, 0); __builtin_amdgcn_s_setprio(0); } while (0)
; #define PG8_WAIT_V(n) asm volatile("s_waitcnt vmcnt(" #n ")" ::: "memory")
; #define PG8_WAIT_L(n) asm volatile("s_waitcnt lgkmcnt(" #n ")" ::: "memory")
; #define PG8_BAR __builtin_amdgcn_s_barrier()
; #define PG8_SCHED __builtin_amdgcn_sched_barrier(0)
; template <class Epi, class Sched, bool ALIGN_EPI = false, bool SP2 = false>
; __device__ __forceinline__ void gemm_phase(PG8_LAS unsigned char* lds, const Gemm g, const Sched& S, const Epi& E, int wave_s) {
;     ...
;             PG8_WAIT_V(8); PG8_WAIT_L(0); PG8_BAR; PG8_MMA(0, 0, At, B0); PG8_MMA(0, 1, At, B1); PG8_BAR; PG8_SCHED;
;             PG8_LDA(At, 0, 1); PG8_STAGE(PG8_SB(0, 0), b2, voffB); PG8_STAGE(PG8_SB(0, 1), b2 + hstepB, voffB); PG8_STAGE(PG8_SA(0, 0), a2, voffA);
;             PG8_WAIT_V(8); PG8_WAIT_L(0); PG8_BAR; PG8_MMA(1, 0, At, B0); PG8_MMA(1, 1, At, B1); PG8_BAR; PG8_SCHED;
	s_setprio 1
	s_waitcnt lgkmcnt(0)
	v_mfma_f32_16x16x32_bf16 v[126:129], v[146:149], v[184:187], v[126:129]
	v_mfma_f32_16x16x32_bf16 v[118:121], v[154:157], v[184:187], v[118:121]
	v_mfma_f32_16x16x32_bf16 v[110:113], v[146:149], v[192:195], v[110:113]
	v_mfma_f32_16x16x32_bf16 v[102:105], v[154:157], v[192:195], v[102:105]
	v_mfma_f32_16x16x32_bf16 v[94:97], v[146:149], v[208:211], v[94:97]
	v_mfma_f32_16x16x32_bf16 v[86:89], v[154:157], v[208:211], v[86:89]
	v_mfma_f32_16x16x32_bf16 v[78:81], v[146:149], v[216:219], v[78:81]
	v_mfma_f32_16x16x32_bf16 v[70:73], v[154:157], v[216:219], v[70:73]
	v_mfma_f32_16x16x32_bf16 v[126:129], v[150:153], v[188:191], v[126:129]
	v_mfma_f32_16x16x32_bf16 v[118:121], v[158:161], v[188:191], v[118:121]
	v_mfma_f32_16x16x32_bf16 v[110:113], v[150:153], v[196:199], v[110:113]
	v_mfma_f32_16x16x32_bf16 v[102:105], v[158:161], v[196:199], v[102:105]
	v_mfma_f32_16x16x32_bf16 v[94:97], v[150:153], v[212:215], v[94:97]
	v_mfma_f32_16x16x32_bf16 v[86:89], v[158:161], v[212:215], v[86:89]
	v_mfma_f32_16x16x32_bf16 v[78:81], v[150:153], v[220:223], v[78:81]
	v_mfma_f32_16x16x32_bf16 v[70:73], v[158:161], v[220:223], v[70:73]
	s_setprio 0
	s_setprio 1
	v_mfma_f32_16x16x32_bf16 v[122:125], v[162:165], v[184:187], v[122:125]
	v_mfma_f32_16x16x32_bf16 v[114:117], v[176:179], v[184:187], v[114:117]
	v_mfma_f32_16x16x32_bf16 v[106:109], v[162:165], v[192:195], v[106:109]
	v_mfma_f32_16x16x32_bf16 v[98:101], v[176:179], v[192:195], v[98:101]
	v_mfma_f32_16x16x32_bf16 v[90:93], v[162:165], v[208:211], v[90:93]
	v_mfma_f32_16x16x32_bf16 v[82:85], v[176:179], v[208:211], v[82:85]
	v_mfma_f32_16x16x32_bf16 v[74:77], v[162:165], v[216:219], v[74:77]
	v_mfma_f32_16x16x32_bf16 v[66:69], v[176:179], v[216:219], v[66:69]
	v_mfma_f32_16x16x32_bf16 v[122:125], v[166:169], v[188:191], v[122:125]
	v_mfma_f32_16x16x32_bf16 v[114:117], v[180:183], v[188:191], v[114:117]
	v_mfma_f32_16x16x32_bf16 v[106:109], v[166:169], v[196:199], v[106:109]
	v_mfma_f32_16x16x32_bf16 v[98:101], v[180:183], v[196:199], v[98:101]
	v_mfma_f32_16x16x32_bf16 v[90:93], v[166:169], v[212:215], v[90:93]
	v_mfma_f32_16x16x32_bf16 v[82:85], v[180:183], v[212:215], v[82:85]
	v_mfma_f32_16x16x32_bf16 v[74:77], v[166:169], v[220:223], v[74:77]
	v_mfma_f32_16x16x32_bf16 v[66:69], v[180:183], v[220:223], v[66:69]
	s_setprio 0
	s_barrier
	s_add_i32 s34, s34, s42
	v_lshl_add_u64 v[140:141], s[20:21], 0, v[0:1]
	s_mov_b32 m0, s34
	ds_read_b128 v[184:187], v145 offset:16384
	ds_read_b128 v[188:191], v145 offset:17408
	ds_read_b128 v[192:195], v145 offset:18432
	ds_read_b128 v[196:199], v145 offset:19456
	ds_read_b128 v[208:211], v145 offset:20480
	ds_read_b128 v[212:215], v145 offset:21504
	ds_read_b128 v[216:219], v145 offset:22528
	ds_read_b128 v[220:223], v145 offset:23552
	global_load_lds_dwordx4 v[140:141], off
	s_add_i32 m0, s34, 0x2000
	s_add_u32 s34, s20, 0x4000
	v_lshl_add_u64 v[170:171], s[20:21], 0, v[130:131]
	s_addc_u32 s35, s21, 0
	s_add_i32 s56, s56, s42
	global_load_lds_dwordx4 v[170:171], off
	v_lshl_add_u64 v[200:201], s[34:35], 0, v[0:1]
	s_mov_b32 m0, s56
	v_lshl_add_u64 v[224:225], s[24:25], 0, v[132:133]
	global_load_lds_dwordx4 v[200:201], off
	v_lshl_add_u64 v[200:201], s[34:35], 0, v[130:131]
	s_add_i32 m0, s56, 0x2000
	s_nop 0
	global_load_lds_dwordx4 v[200:201], off
	v_lshl_add_u64 v[200:201], s[24:25], 0, v[134:135]
	s_mov_b32 m0, s43
	s_nop 0
	global_load_lds_dwordx4 v[200:201], off
	s_mov_b32 m0, s44
	s_nop 0
	global_load_lds_dwordx4 v[224:225], off
	s_waitcnt vmcnt(8)
	s_waitcnt lgkmcnt(0)
	s_barrier
	s_setprio 1
	s_waitcnt lgkmcnt(0)
	v_mfma_f32_16x16x32_bf16 v[62:65], v[146:149], v[184:187], v[62:65]
	v_mfma_f32_16x16x32_bf16 v[54:57], v[154:157], v[184:187], v[54:57]
	v_mfma_f32_16x16x32_bf16 v[46:49], v[146:149], v[192:195], v[46:49]
	v_mfma_f32_16x16x32_bf16 v[38:41], v[154:157], v[192:195], v[38:41]
	v_mfma_f32_16x16x32_bf16 v[30:33], v[146:149], v[208:211], v[30:33]
	v_mfma_f32_16x16x32_bf16 v[22:25], v[154:157], v[208:211], v[22:25]
	v_mfma_f32_16x16x32_bf16 v[14:17], v[146:149], v[216:219], v[14:17]
	v_mfma_f32_16x16x32_bf16 v[6:9], v[154:157], v[216:219], v[6:9]
	v_mfma_f32_16x16x32_bf16 v[62:65], v[150:153], v[188:191], v[62:65]
	v_mfma_f32_16x16x32_bf16 v[54:57], v[158:161], v[188:191], v[54:57]
	v_mfma_f32_16x16x32_bf16 v[46:49], v[150:153], v[196:199], v[46:49]
	v_mfma_f32_16x16x32_bf16 v[38:41], v[158:161], v[196:199], v[38:41]
	v_mfma_f32_16x16x32_bf16 v[30:33], v[150:153], v[212:215], v[30:33]
	v_mfma_f32_16x16x32_bf16 v[22:25], v[158:161], v[212:215], v[22:25]
	v_mfma_f32_16x16x32_bf16 v[14:17], v[150:153], v[220:223], v[14:17]
	v_mfma_f32_16x16x32_bf16 v[6:9], v[158:161], v[220:223], v[6:9]
	s_setprio 0
	s_setprio 1
	v_mfma_f32_16x16x32_bf16 v[58:61], v[162:165], v[184:187], v[58:61]
	v_mfma_f32_16x16x32_bf16 v[50:53], v[176:179], v[184:187], v[50:53]
	v_mfma_f32_16x16x32_bf16 v[42:45], v[162:165], v[192:195], v[42:45]
	v_mfma_f32_16x16x32_bf16 v[34:37], v[176:179], v[192:195], v[34:37]
	v_mfma_f32_16x16x32_bf16 v[26:29], v[162:165], v[208:211], v[26:29]
	v_mfma_f32_16x16x32_bf16 v[18:21], v[176:179], v[208:211], v[18:21]
	v_mfma_f32_16x16x32_bf16 v[10:13], v[162:165], v[216:219], v[10:13]
	v_mfma_f32_16x16x32_bf16 v[2:5], v[176:179], v[216:219], v[2:5]
	v_mfma_f32_16x16x32_bf16 v[58:61], v[166:169], v[188:191], v[58:61]
	v_mfma_f32_16x16x32_bf16 v[50:53], v[180:183], v[188:191], v[50:53]
	v_mfma_f32_16x16x32_bf16 v[42:45], v[166:169], v[196:199], v[42:45]
	v_mfma_f32_16x16x32_bf16 v[34:37], v[180:183], v[196:199], v[34:37]
	v_mfma_f32_16x16x32_bf16 v[26:29], v[166:169], v[212:215], v[26:29]
	v_mfma_f32_16x16x32_bf16 v[18:21], v[180:183], v[212:215], v[18:21]
	v_mfma_f32_16x16x32_bf16 v[10:13], v[166:169], v[220:223], v[10:13]
	v_mfma_f32_16x16x32_bf16 v[2:5], v[180:183], v[220:223], v[2:5]
	s_setprio 0
	s_barrier
; #define PG8_STAGE(bufoff, gbase, voff) do { _Pragma("unroll") for (int _i = 0; _i < 2; ++_i) \
;         __builtin_amdgcn_global_load_lds((const unsigned*)((const char*)(gbase) + (voff)[_i]), (PG8_LAS unsigned*)(lds + (bufoff) + ldsw + _i * 8192), 16, 0, 0); } while (0)
; #define PG8_LDA(dst, b, h) do { _Pragma("unroll") for (int m = 0; m < 4; ++m) _Pragma("unroll") for (int k = 0; k < 2; ++k) dst[m][k] = *(const PG8_LAS bf16x8*)(lds + PG8_SA(b, h) + aoff + m * 2048 + k * 1024); } while (0)
; #define PG8_LDB(dst, b, h) do { _Pragma("unroll") for (int n = 0; n < 2; ++n) _Pragma("unroll") for (int k = 0; k < 2; ++k) dst[n][k] = *(const PG8_LAS bf16x8*)(lds + PG8_SB(b, h) + boff + n * 2048 + k * 1024); } while (0)
; #define PG8_MMA(ai, bj, At, Bt) do { __builtin_amdgcn_s_setprio(1); _Pragma("unroll") for (int m = 0; m < 4; ++m) _Pragma("unroll") for (int n = 0; n < 2; ++n) _Pragma("unroll") for (int k = 0; k < 2; ++k) \
;         acc[ai][bj][m][n] = __builtin_amdgcn_mfma_f32_16x16x32_bf16(Bt[n][k], At[m][k], acc[ai][bj][m][n], 0, 0, 0); __builtin_amdgcn_s_setprio(0); } while (0)
; #define PG8_WAIT_V(n) asm volatile("s_waitcnt vmcnt(" #n ")" ::: "memory")
; #define PG8_WAIT_L(n) asm volatile("s_waitcnt lgkmcnt(" #n ")" ::: "memory")
; #define PG8_BAR __builtin_amdgcn_s_barrier()
; #define PG8_SCHED __builtin_amdgcn_sched_barrier(0)
; template <class Epi, class Sched, bool ALIGN_EPI = false, bool SP2 = false>
; __device__ __forceinline__ void gemm_phase(PG8_LAS unsigned char* lds, const Gemm g, const Sched& S, const Epi& E, int wave_s) {
;     ...
;             PG8_LDB(B0, 1, 0); PG8_LDB(B1, 1, 1); PG8_SCHED; PG8_LDA(At, 1, 0); PG8_STAGE(PG8_SA(0, 1), a2 + hstepA, voffA);
;             PG8_WAIT_V(8); PG8_WAIT_L(0); PG8_BAR; PG8_MMA(0, 0, At, B0); PG8_MMA(0, 1, At, B1); PG8_BAR; PG8_SCHED;
	s_add_i32 s34, 0, 0x18000
	s_add_i32 s35, 0, 0x1c000
	v_add_u32_e32 v158, s34, v143
	v_add_u32_e32 v180, s35, v143
	ds_read_b128 v[146:149], v158
	ds_read_b128 v[150:153], v158 offset:1024
	ds_read_b128 v[154:157], v158 offset:2048
	ds_read_b128 v[158:161], v158 offset:3072
	ds_read_b128 v[162:165], v180
	ds_read_b128 v[166:169], v180 offset:1024
	ds_read_b128 v[176:179], v180 offset:2048
	ds_read_b128 v[180:183], v180 offset:3072
	s_add_u32 s24, s24, 0x4000
	s_addc_u32 s25, s25, 0
	s_mov_b32 m0, s45
	v_lshl_add_u64 v[226:227], s[24:25], 0, v[134:135]
	ds_read_b128 v[184:187], v145 offset:32768
	ds_read_b128 v[188:191], v145 offset:33792
	ds_read_b128 v[192:195], v145 offset:34816
	ds_read_b128 v[196:199], v145 offset:35840
	ds_read_b128 v[208:211], v145 offset:36864
	ds_read_b128 v[212:215], v145 offset:37888
	ds_read_b128 v[216:219], v145 offset:38912
	ds_read_b128 v[220:223], v145 offset:39936
	global_load_lds_dwordx4 v[226:227], off
	v_lshl_add_u64 v[226:227], s[24:25], 0, v[132:133]
	s_mov_b32 m0, s46
	s_nop 0
	global_load_lds_dwordx4 v[226:227], off
	s_waitcnt vmcnt(8)
	s_waitcnt lgkmcnt(0)
	s_barrier
	s_setprio 1
	s_waitcnt lgkmcnt(0)
	v_mfma_f32_16x16x32_bf16 v[126:129], v[146:149], v[184:187], v[126:129]
	v_mfma_f32_16x16x32_bf16 v[118:121], v[154:157], v[184:187], v[118:121]
	v_mfma_f32_16x16x32_bf16 v[110:113], v[146:149], v[192:195], v[110:113]
	v_mfma_f32_16x16x32_bf16 v[102:105], v[154:157], v[192:195], v[102:105]
	v_mfma_f32_16x16x32_bf16 v[94:97], v[146:149], v[208:211], v[94:97]
	v_mfma_f32_16x16x32_bf16 v[86:89], v[154:157], v[208:211], v[86:89]
	v_mfma_f32_16x16x32_bf16 v[78:81], v[146:149], v[216:219], v[78:81]
	v_mfma_f32_16x16x32_bf16 v[70:73], v[154:157], v[216:219], v[70:73]
	v_mfma_f32_16x16x32_bf16 v[126:129], v[150:153], v[188:191], v[126:129]
	v_mfma_f32_16x16x32_bf16 v[118:121], v[158:161], v[188:191], v[118:121]
	v_mfma_f32_16x16x32_bf16 v[110:113], v[150:153], v[196:199], v[110:113]
	v_mfma_f32_16x16x32_bf16 v[102:105], v[158:161], v[196:199], v[102:105]
	v_mfma_f32_16x16x32_bf16 v[94:97], v[150:153], v[212:215], v[94:97]
	v_mfma_f32_16x16x32_bf16 v[86:89], v[158:161], v[212:215], v[86:89]
	v_mfma_f32_16x16x32_bf16 v[78:81], v[150:153], v[220:223], v[78:81]
	v_mfma_f32_16x16x32_bf16 v[70:73], v[158:161], v[220:223], v[70:73]
	s_setprio 0
	s_setprio 1
	v_mfma_f32_16x16x32_bf16 v[122:125], v[162:165], v[184:187], v[122:125]
	v_mfma_f32_16x16x32_bf16 v[114:117], v[176:179], v[184:187], v[114:117]
	v_mfma_f32_16x16x32_bf16 v[106:109], v[162:165], v[192:195], v[106:109]
	v_mfma_f32_16x16x32_bf16 v[98:101], v[176:179], v[192:195], v[98:101]
	v_mfma_f32_16x16x32_bf16 v[90:93], v[162:165], v[208:211], v[90:93]
	v_mfma_f32_16x16x32_bf16 v[82:85], v[176:179], v[208:211], v[82:85]
	v_mfma_f32_16x16x32_bf16 v[74:77], v[162:165], v[216:219], v[74:77]
	v_mfma_f32_16x16x32_bf16 v[66:69], v[176:179], v[216:219], v[66:69]
	v_mfma_f32_16x16x32_bf16 v[122:125], v[166:169], v[188:191], v[122:125]
	v_mfma_f32_16x16x32_bf16 v[114:117], v[180:183], v[188:191], v[114:117]
	v_mfma_f32_16x16x32_bf16 v[106:109], v[166:169], v[196:199], v[106:109]
	v_mfma_f32_16x16x32_bf16 v[98:101], v[180:183], v[196:199], v[98:101]
	v_mfma_f32_16x16x32_bf16 v[90:93], v[166:169], v[212:215], v[90:93]
	v_mfma_f32_16x16x32_bf16 v[82:85], v[180:183], v[212:215], v[82:85]
	v_mfma_f32_16x16x32_bf16 v[74:77], v[166:169], v[220:223], v[74:77]
	v_mfma_f32_16x16x32_bf16 v[66:69], v[180:183], v[220:223], v[66:69]
	s_setprio 0
	s_barrier
; #define PG8_STAGE(bufoff, gbase, voff) do { _Pragma("unroll") for (int _i = 0; _i < 2; ++_i) \
;         __builtin_amdgcn_global_load_lds((const unsigned*)((const char*)(gbase) + (voff)[_i]), (PG8_LAS unsigned*)(lds + (bufoff) + ldsw + _i * 8192), 16, 0, 0); } while (0)
; #define PG8_LDA(dst, b, h) do { _Pragma("unroll") for (int m = 0; m < 4; ++m) _Pragma("unroll") for (int k = 0; k < 2; ++k) dst[m][k] = *(const PG8_LAS bf16x8*)(lds + PG8_SA(b, h) + aoff + m * 2048 + k * 1024); } while (0)
; #define PG8_WAIT_V(n) asm volatile("s_waitcnt vmcnt(" #n ")" ::: "memory")
; #define PG8_BAR __builtin_amdgcn_s_barrier()
; template <class Epi, class Sched, bool ALIGN_EPI = false, bool SP2 = false>
; __device__ __forceinline__ void gemm_phase(PG8_LAS unsigned char* lds, const Gemm g, const Sched& S, const Epi& E, int wave_s) {
;     ...
;         for (int t = 0; t < nt; t += 2) {
;             const bool last = (t == nt - 2);
;             const char* a1 = cA + (size_t)(t + 1) * kstep;
;             const char* a2 = last ? nA : cA + (size_t)(t + 2) * kstep; const char* b2 = last ? nB : cB + (size_t)(t + 2) * kstep;
;             const char* a3 = a2 + kstep; const char* b3 = b2 + kstep;
;             if (last && has_next) S.a_ready(nxt);
;             if constexpr (Epi::HAS_MID) { if (t == nt / 2) E.mid(acc, cur, wr, wc, fr, fq); }
;             if constexpr (SP2) {
;             PG8_LDB(B0, 0, 0); PG8_LDB(B1, 0, 1); PG8_SCHED; PG8_LDA(At, 0, 0); PG8_STAGE(PG8_SA(1, 1), a1 + hstepA, voffA);
;             PG8_WAIT_V(8); PG8_WAIT_L(0); PG8_BAR; PG8_MMA(0, 0, At, B0); PG8_MMA(0, 1, At, B1); PG8_BAR; PG8_SCHED;
;             PG8_LDA(At, 0, 1); PG8_STAGE(PG8_SB(0, 0), b2, voffB); PG8_STAGE(PG8_SB(0, 1), b2 + hstepB, voffB); PG8_STAGE(PG8_SA(0, 0), a2, voffA);
;             PG8_WAIT_V(8); PG8_WAIT_L(0); PG8_BAR; PG8_MMA(1, 0, At, B0); PG8_MMA(1, 1, At, B1); PG8_BAR; PG8_SCHED;
;             PG8_LDB(B0, 1, 0); PG8_LDB(B1, 1, 1); PG8_SCHED; PG8_LDA(At, 1, 0); PG8_STAGE(PG8_SA(0, 1), a2 + hstepA, voffA);
;             PG8_WAIT_V(8); PG8_WAIT_L(0); PG8_BAR; PG8_MMA(0, 0, At, B0); PG8_MMA(0, 1, At, B1); PG8_BAR; PG8_SCHED;
;             PG8_LDA(At, 1, 1); PG8_STAGE(PG8_SB(1, 0), b3, voffB); PG8_STAGE(PG8_SB(1, 1), b3 + hstepB, voffB); PG8_STAGE(PG8_SA(1, 0), a3, voffA);
;             PG8_WAIT_V(8); PG8_WAIT_L(0); PG8_BAR; PG8_MMA(1, 0, At, B0); PG8_MMA(1, 1, At, B1); PG8_BAR; PG8_SCHED;
	s_add_i32 s24, s34, s42
	s_mov_b64 s[100:101], 0x8000
	v_lshl_add_u64 v[140:141], v[140:141], 0, s[100:101]
	s_mov_b32 m0, s24
	ds_read_b128 v[184:187], v145 offset:49152
	ds_read_b128 v[188:191], v145 offset:50176
	ds_read_b128 v[192:195], v145 offset:51200
	ds_read_b128 v[196:199], v145 offset:52224
	ds_read_b128 v[208:211], v145 offset:53248
	ds_read_b128 v[212:215], v145 offset:54272
	ds_read_b128 v[216:219], v145 offset:55296
	ds_read_b128 v[220:223], v145 offset:56320
	global_load_lds_dwordx4 v[140:141], off
	s_add_i32 m0, s24, 0x2000
	s_add_u32 s20, s20, 0xc000
	v_lshl_add_u64 v[140:141], v[170:171], 0, s[100:101]
	s_addc_u32 s21, s21, 0
	s_add_i32 s24, s35, s42
	global_load_lds_dwordx4 v[140:141], off
	v_lshl_add_u64 v[140:141], s[20:21], 0, v[0:1]
	s_mov_b32 m0, s24
	s_nop 0
	global_load_lds_dwordx4 v[140:141], off
	v_lshl_add_u64 v[140:141], s[20:21], 0, v[130:131]
	s_add_i32 m0, s24, 0x2000
	s_nop 0
	global_load_lds_dwordx4 v[140:141], off
	s_mov_b64 s[100:101], 0x8000
	v_lshl_add_u64 v[140:141], v[200:201], 0, s[100:101]
	s_mov_b32 m0, s47
	s_nop 0
	global_load_lds_dwordx4 v[140:141], off
	v_lshl_add_u64 v[140:141], v[224:225], 0, s[100:101]
	s_mov_b32 m0, s48
	s_nop 0
	global_load_lds_dwordx4 v[140:141], off
	s_waitcnt vmcnt(8)
	s_waitcnt lgkmcnt(0)
	s_barrier
	s_setprio 1
	s_waitcnt lgkmcnt(0)
	v_mfma_f32_16x16x32_bf16 v[62:65], v[146:149], v[184:187], v[62:65]
	v_mfma_f32_16x16x32_bf16 v[54:57], v[154:157], v[184:187], v[54:57]
	v_mfma_f32_16x16x32_bf16 v[46:49], v[146:149], v[192:195], v[46:49]
	v_mfma_f32_16x16x32_bf16 v[38:41], v[154:157], v[192:195], v[38:41]
	v_mfma_f32_16x16x32_bf16 v[30:33], v[146:149], v[208:211], v[30:33]
	v_mfma_f32_16x16x32_bf16 v[22:25], v[154:157], v[208:211], v[22:25]
	v_mfma_f32_16x16x32_bf16 v[14:17], v[146:149], v[216:219], v[14:17]
	v_mfma_f32_16x16x32_bf16 v[6:9], v[154:157], v[216:219], v[6:9]
	v_mfma_f32_16x16x32_bf16 v[62:65], v[150:153], v[188:191], v[62:65]
	v_mfma_f32_16x16x32_bf16 v[54:57], v[158:161], v[188:191], v[54:57]
	v_mfma_f32_16x16x32_bf16 v[46:49], v[150:153], v[196:199], v[46:49]
	v_mfma_f32_16x16x32_bf16 v[38:41], v[158:161], v[196:199], v[38:41]
	v_mfma_f32_16x16x32_bf16 v[30:33], v[150:153], v[212:215], v[30:33]
	v_mfma_f32_16x16x32_bf16 v[22:25], v[158:161], v[212:215], v[22:25]
	v_mfma_f32_16x16x32_bf16 v[14:17], v[150:153], v[220:223], v[14:17]
	v_mfma_f32_16x16x32_bf16 v[6:9], v[158:161], v[220:223], v[6:9]
	s_setprio 0
	s_setprio 1
	v_mfma_f32_16x16x32_bf16 v[58:61], v[162:165], v[184:187], v[58:61]
	v_mfma_f32_16x16x32_bf16 v[50:53], v[176:179], v[184:187], v[50:53]
	v_mfma_f32_16x16x32_bf16 v[42:45], v[162:165], v[192:195], v[42:45]
	v_mfma_f32_16x16x32_bf16 v[34:37], v[176:179], v[192:195], v[34:37]
	v_mfma_f32_16x16x32_bf16 v[26:29], v[162:165], v[208:211], v[26:29]
	v_mfma_f32_16x16x32_bf16 v[18:21], v[176:179], v[208:211], v[18:21]
	v_mfma_f32_16x16x32_bf16 v[10:13], v[162:165], v[216:219], v[10:13]
	v_mfma_f32_16x16x32_bf16 v[2:5], v[176:179], v[216:219], v[2:5]
	v_mfma_f32_16x16x32_bf16 v[58:61], v[166:169], v[188:191], v[58:61]
	v_mfma_f32_16x16x32_bf16 v[50:53], v[180:183], v[188:191], v[50:53]
	v_mfma_f32_16x16x32_bf16 v[42:45], v[166:169], v[196:199], v[42:45]
	v_mfma_f32_16x16x32_bf16 v[34:37], v[180:183], v[196:199], v[34:37]
	v_mfma_f32_16x16x32_bf16 v[26:29], v[166:169], v[212:215], v[26:29]
	v_mfma_f32_16x16x32_bf16 v[18:21], v[180:183], v[212:215], v[18:21]
	v_mfma_f32_16x16x32_bf16 v[10:13], v[166:169], v[220:223], v[10:13]
	v_mfma_f32_16x16x32_bf16 v[2:5], v[180:183], v[220:223], v[2:5]
	s_setprio 0
	s_barrier
	s_add_i32 s55, s55, 2
	s_add_u32 s51, s51, 0x10000
	s_addc_u32 s54, s54, 0
	s_add_u32 s18, s18, 0x10000
	s_addc_u32 s19, s19, 0
	s_cmp_gt_u32 s55, 29
	s_cbranch_scc0 .LBB0_1797
	s_and_b64 vcc, exec, s[8:9]
	s_cbranch_vccz .LBB0_1800
	s_barrier
